# R waves: counted lgkmcnt(2) at the interval-end barrier (y write issued before the last two next-buffer reads); step-0 Q wait 9
# speedup vs baseline: 1.0076x; 1.0076x over previous
; #define LAS __attribute__((address_space(3)))
; template <int CTRL> __device__ __forceinline__ float dppf(float v) { return __builtin_bit_cast(float, __builtin_amdgcn_update_dpp(0, __builtin_bit_cast(int, v), CTRL, 0xF, 0xF, true)); }
; #define LO2(v) __builtin_shufflevector(v, v, 0, 1)
; #define HI2(v) __builtin_shufflevector(v, v, 2, 3)
; __device__ __forceinline__ void phase_scan(const Args& a, LAS unsigned char* lds) {
;     ...
;                 for (int s = 0; s < TC; ++s) {
;                     const LAS float* o = obase + (s + 1) * 320;
;                     const f32x4 now = *(const LAS f32x4*)(o), noa = *(const LAS f32x4*)(o + 4), nob = *(const LAS f32x4*)(o + 8), nok = *(const LAS f32x4*)(o + 12), norr = *(const LAS f32x4*)(o + 16);
;                     const f32x2 nvv = *(const LAS f32x2*)(vbase + (s + 1) * 64);
;                     const f32x2 p = pkfma_b<1>(C3, HI2(oa), pkfma_b<0>(C2, HI2(oa), pkfma_b<1>(C1, LO2(oa), pkmul_b<0>(C0, LO2(oa)))));
;                     float sa0 = p.x, sa1 = p.y;
;                     sa0 = reduce16(sa0); asm volatile("" : "+v"(sa0)); sa1 = reduce16(sa1);
;                     const f32x2 sap = {sa0, sa1};
;                     C0 = pkfma_b<0>(vv, LO2(ok), pkfma_b<0>(sap, LO2(ob), pkmul_b<0>(C0, LO2(ow))));
;                     C1 = pkfma_b<1>(vv, LO2(ok), pkfma_b<1>(sap, LO2(ob), pkmul_b<1>(C1, LO2(ow))));
;                     C2 = pkfma_b<0>(vv, HI2(ok), pkfma_b<0>(sap, HI2(ob), pkmul_b<0>(C2, HI2(ow))));
;                     C3 = pkfma_b<1>(vv, HI2(ok), pkfma_b<1>(sap, HI2(ob), pkmul_b<1>(C3, HI2(ow))));
;                     const f32x2 q = pkfma_b<1>(C3, HI2(orr), pkfma_b<0>(C2, HI2(orr), pkfma_b<1>(C1, LO2(orr), pkmul_b<0>(C0, LO2(orr)))));
;                     float y0 = q.x, y1 = q.y;
;                     y0 += dppf<0xB1>(y0); y1 += dppf<0xB1>(y1);
;                     *(LAS f32x2*)(yb + ((s * 32 + (r0 >> 1)) * 8 + ((lane >> 1) & 7)) * 2) = (f32x2){y0, y1};
;                     ow = now; oa = noa; ob = nob; ok = nok; orr = norr; vv = nvv;
;                 }
.LW_rloop:
	s_waitcnt lgkmcnt(10)
	v_pk_mul_f32 v[168:169], v[236:237], v[100:101] op_sel_hi:[1,0]
	v_pk_mul_f32 v[170:171], v[238:239], v[100:101] op_sel:[0,1]
	v_pk_fma_f32 v[168:169], v[240:241], v[102:103], v[168:169] op_sel_hi:[1,0,1]
	v_pk_fma_f32 v[170:171], v[242:243], v[102:103], v[170:171] op_sel:[0,1,0]
	v_pk_fma_f32 v[168:169], v[244:245], v[104:105], v[168:169] op_sel_hi:[1,0,1]
	v_pk_fma_f32 v[170:171], v[246:247], v[104:105], v[170:171] op_sel:[0,1,0]
	v_pk_fma_f32 v[168:169], v[248:249], v[106:107], v[168:169] op_sel_hi:[1,0,1]
	v_pk_fma_f32 v[170:171], v[250:251], v[106:107], v[170:171] op_sel:[0,1,0]
	ds_read_b128 v[100:103], v252 offset:1296
	ds_read_b128 v[104:107], v252 offset:1376
	v_pk_add_f32 v[168:169], v[168:169], v[170:171]
	s_waitcnt lgkmcnt(10)
	v_pk_mul_f32 v[236:237], v[236:237], v[108:109] op_sel_hi:[1,0]
	v_pk_mul_f32 v[238:239], v[238:239], v[108:109] op_sel:[0,1]
	v_pk_mul_f32 v[240:241], v[240:241], v[110:111] op_sel_hi:[1,0]
	v_pk_mul_f32 v[242:243], v[242:243], v[110:111] op_sel:[0,1]
	v_pk_mul_f32 v[244:245], v[244:245], v[112:113] op_sel_hi:[1,0]
	v_pk_mul_f32 v[246:247], v[246:247], v[112:113] op_sel:[0,1]
	v_pk_mul_f32 v[248:249], v[248:249], v[114:115] op_sel_hi:[1,0]
	v_pk_mul_f32 v[250:251], v[250:251], v[114:115] op_sel:[0,1]
	v_add_f32_dpp v168, v168, v168 quad_perm:[1,0,3,2] row_mask:0xf bank_mask:0xf bound_ctrl:1
	v_add_f32_dpp v169, v169, v169 quad_perm:[1,0,3,2] row_mask:0xf bank_mask:0xf bound_ctrl:1
	ds_read_b128 v[108:111], v252 offset:1280
	v_add_f32_dpp v168, v168, v168 quad_perm:[2,3,0,1] row_mask:0xf bank_mask:0xf bound_ctrl:1
	v_add_f32_dpp v169, v169, v169 quad_perm:[2,3,0,1] row_mask:0xf bank_mask:0xf bound_ctrl:1
	ds_read_b128 v[112:115], v252 offset:1360
	v_add_f32_dpp v168, v168, v168 row_half_mirror row_mask:0xf bank_mask:0xf bound_ctrl:1
	v_add_f32_dpp v169, v169, v169 row_half_mirror row_mask:0xf bank_mask:0xf bound_ctrl:1
	s_waitcnt lgkmcnt(10)
	v_pk_fma_f32 v[236:237], v[168:169], v[116:117], v[236:237] op_sel_hi:[1,0,1]
	v_pk_fma_f32 v[238:239], v[168:169], v[116:117], v[238:239] op_sel:[0,1,0]
	v_pk_fma_f32 v[240:241], v[168:169], v[118:119], v[240:241] op_sel_hi:[1,0,1]
	v_pk_fma_f32 v[242:243], v[168:169], v[118:119], v[242:243] op_sel:[0,1,0]
	v_pk_fma_f32 v[244:245], v[168:169], v[120:121], v[244:245] op_sel_hi:[1,0,1]
	v_pk_fma_f32 v[246:247], v[168:169], v[120:121], v[246:247] op_sel:[0,1,0]
	v_pk_fma_f32 v[248:249], v[168:169], v[122:123], v[248:249] op_sel_hi:[1,0,1]
	v_pk_fma_f32 v[250:251], v[168:169], v[122:123], v[250:251] op_sel:[0,1,0]
	ds_read_b128 v[116:119], v252 offset:1312
	ds_read_b128 v[120:123], v252 offset:1392
	s_waitcnt lgkmcnt(9)
	v_pk_fma_f32 v[236:237], v[166:167], v[124:125], v[236:237] op_sel_hi:[1,0,1]
	v_pk_fma_f32 v[238:239], v[166:167], v[124:125], v[238:239] op_sel:[0,1,0]
	v_pk_fma_f32 v[240:241], v[166:167], v[126:127], v[240:241] op_sel_hi:[1,0,1]
	v_pk_fma_f32 v[242:243], v[166:167], v[126:127], v[242:243] op_sel:[0,1,0]
	v_pk_fma_f32 v[244:245], v[166:167], v[128:129], v[244:245] op_sel_hi:[1,0,1]
	v_pk_fma_f32 v[246:247], v[166:167], v[128:129], v[246:247] op_sel:[0,1,0]
	v_pk_fma_f32 v[248:249], v[166:167], v[130:131], v[248:249] op_sel_hi:[1,0,1]
	v_pk_fma_f32 v[250:251], v[166:167], v[130:131], v[250:251] op_sel:[0,1,0]
	ds_read_b128 v[124:127], v252 offset:1328
	ds_read_b128 v[128:131], v252 offset:1408
	ds_read_b64 v[166:167], v253 offset:256
	s_waitcnt lgkmcnt(9)
	v_pk_mul_f32 v[172:173], v[236:237], v[132:133] op_sel_hi:[1,0]
	v_pk_mul_f32 v[174:175], v[238:239], v[132:133] op_sel:[0,1]
	v_pk_fma_f32 v[172:173], v[240:241], v[134:135], v[172:173] op_sel_hi:[1,0,1]
	v_pk_fma_f32 v[174:175], v[242:243], v[134:135], v[174:175] op_sel:[0,1,0]
	v_pk_fma_f32 v[172:173], v[244:245], v[136:137], v[172:173] op_sel_hi:[1,0,1]
	v_pk_fma_f32 v[174:175], v[246:247], v[136:137], v[174:175] op_sel:[0,1,0]
	v_pk_fma_f32 v[172:173], v[248:249], v[138:139], v[172:173] op_sel_hi:[1,0,1]
	v_pk_fma_f32 v[174:175], v[250:251], v[138:139], v[174:175] op_sel:[0,1,0]
	ds_read_b128 v[132:135], v252 offset:1344
	ds_read_b128 v[136:139], v252 offset:1424
	v_pk_add_f32 v[172:173], v[172:173], v[174:175]
	ds_write_b64 v254, v[172:173]
	s_waitcnt lgkmcnt(10)
	v_pk_mul_f32 v[168:169], v[236:237], v[100:101] op_sel_hi:[1,0]
	v_pk_mul_f32 v[170:171], v[238:239], v[100:101] op_sel:[0,1]
	v_pk_fma_f32 v[168:169], v[240:241], v[102:103], v[168:169] op_sel_hi:[1,0,1]
	v_pk_fma_f32 v[170:171], v[242:243], v[102:103], v[170:171] op_sel:[0,1,0]
	v_pk_fma_f32 v[168:169], v[244:245], v[104:105], v[168:169] op_sel_hi:[1,0,1]
	v_pk_fma_f32 v[170:171], v[246:247], v[104:105], v[170:171] op_sel:[0,1,0]
	v_pk_fma_f32 v[168:169], v[248:249], v[106:107], v[168:169] op_sel_hi:[1,0,1]
	v_pk_fma_f32 v[170:171], v[250:251], v[106:107], v[170:171] op_sel:[0,1,0]
	ds_read_b128 v[100:103], v252 offset:2576
	ds_read_b128 v[104:107], v252 offset:2656
	v_pk_add_f32 v[168:169], v[168:169], v[170:171]
	s_waitcnt lgkmcnt(10)
	v_pk_mul_f32 v[236:237], v[236:237], v[108:109] op_sel_hi:[1,0]
	v_pk_mul_f32 v[238:239], v[238:239], v[108:109] op_sel:[0,1]
	v_pk_mul_f32 v[240:241], v[240:241], v[110:111] op_sel_hi:[1,0]
	v_pk_mul_f32 v[242:243], v[242:243], v[110:111] op_sel:[0,1]
	v_pk_mul_f32 v[244:245], v[244:245], v[112:113] op_sel_hi:[1,0]
	v_pk_mul_f32 v[246:247], v[246:247], v[112:113] op_sel:[0,1]
	v_pk_mul_f32 v[248:249], v[248:249], v[114:115] op_sel_hi:[1,0]
	v_pk_mul_f32 v[250:251], v[250:251], v[114:115] op_sel:[0,1]
	v_add_f32_dpp v168, v168, v168 quad_perm:[1,0,3,2] row_mask:0xf bank_mask:0xf bound_ctrl:1
	v_add_f32_dpp v169, v169, v169 quad_perm:[1,0,3,2] row_mask:0xf bank_mask:0xf bound_ctrl:1
	ds_read_b128 v[108:111], v252 offset:2560
	v_add_f32_dpp v168, v168, v168 quad_perm:[2,3,0,1] row_mask:0xf bank_mask:0xf bound_ctrl:1
	v_add_f32_dpp v169, v169, v169 quad_perm:[2,3,0,1] row_mask:0xf bank_mask:0xf bound_ctrl:1
	ds_read_b128 v[112:115], v252 offset:2640
	v_add_f32_dpp v168, v168, v168 row_half_mirror row_mask:0xf bank_mask:0xf bound_ctrl:1
	v_add_f32_dpp v169, v169, v169 row_half_mirror row_mask:0xf bank_mask:0xf bound_ctrl:1
	s_waitcnt lgkmcnt(10)
; #define LAS __attribute__((address_space(3)))
; template <int CTRL> __device__ __forceinline__ float dppf(float v) { return __builtin_bit_cast(float, __builtin_amdgcn_update_dpp(0, __builtin_bit_cast(int, v), CTRL, 0xF, 0xF, true)); }
; #define LO2(v) __builtin_shufflevector(v, v, 0, 1)
; #define HI2(v) __builtin_shufflevector(v, v, 2, 3)
; __device__ __forceinline__ void phase_scan(const Args& a, LAS unsigned char* lds) {
;     ...
;                 for (int s = 0; s < TC; ++s) {
;                     const LAS float* o = obase + (s + 1) * 320;
;                     const f32x4 now = *(const LAS f32x4*)(o), noa = *(const LAS f32x4*)(o + 4), nob = *(const LAS f32x4*)(o + 8), nok = *(const LAS f32x4*)(o + 12), norr = *(const LAS f32x4*)(o + 16);
;                     const f32x2 nvv = *(const LAS f32x2*)(vbase + (s + 1) * 64);
;                     const f32x2 p = pkfma_b<1>(C3, HI2(oa), pkfma_b<0>(C2, HI2(oa), pkfma_b<1>(C1, LO2(oa), pkmul_b<0>(C0, LO2(oa)))));
;                     float sa0 = p.x, sa1 = p.y;
;                     sa0 = reduce16(sa0); asm volatile("" : "+v"(sa0)); sa1 = reduce16(sa1);
;                     const f32x2 sap = {sa0, sa1};
;                     C0 = pkfma_b<0>(vv, LO2(ok), pkfma_b<0>(sap, LO2(ob), pkmul_b<0>(C0, LO2(ow))));
;                     C1 = pkfma_b<1>(vv, LO2(ok), pkfma_b<1>(sap, LO2(ob), pkmul_b<1>(C1, LO2(ow))));
;                     C2 = pkfma_b<0>(vv, HI2(ok), pkfma_b<0>(sap, HI2(ob), pkmul_b<0>(C2, HI2(ow))));
;                     C3 = pkfma_b<1>(vv, HI2(ok), pkfma_b<1>(sap, HI2(ob), pkmul_b<1>(C3, HI2(ow))));
;                     const f32x2 q = pkfma_b<1>(C3, HI2(orr), pkfma_b<0>(C2, HI2(orr), pkfma_b<1>(C1, LO2(orr), pkmul_b<0>(C0, LO2(orr)))));
;                     float y0 = q.x, y1 = q.y;
;                     y0 += dppf<0xB1>(y0); y1 += dppf<0xB1>(y1);
;                     *(LAS f32x2*)(yb + ((s * 32 + (r0 >> 1)) * 8 + ((lane >> 1) & 7)) * 2) = (f32x2){y0, y1};
;                     ow = now; oa = noa; ob = nob; ok = nok; orr = norr; vv = nvv;
;                 }
	v_pk_fma_f32 v[236:237], v[168:169], v[116:117], v[236:237] op_sel_hi:[1,0,1]
	v_pk_fma_f32 v[238:239], v[168:169], v[116:117], v[238:239] op_sel:[0,1,0]
	v_pk_fma_f32 v[240:241], v[168:169], v[118:119], v[240:241] op_sel_hi:[1,0,1]
	v_pk_fma_f32 v[242:243], v[168:169], v[118:119], v[242:243] op_sel:[0,1,0]
	v_pk_fma_f32 v[244:245], v[168:169], v[120:121], v[244:245] op_sel_hi:[1,0,1]
	v_pk_fma_f32 v[246:247], v[168:169], v[120:121], v[246:247] op_sel:[0,1,0]
	v_pk_fma_f32 v[248:249], v[168:169], v[122:123], v[248:249] op_sel_hi:[1,0,1]
	v_pk_fma_f32 v[250:251], v[168:169], v[122:123], v[250:251] op_sel:[0,1,0]
	ds_read_b128 v[116:119], v252 offset:2592
	ds_read_b128 v[120:123], v252 offset:2672
	s_waitcnt lgkmcnt(9)
	v_pk_fma_f32 v[236:237], v[166:167], v[124:125], v[236:237] op_sel_hi:[1,0,1]
	v_pk_fma_f32 v[238:239], v[166:167], v[124:125], v[238:239] op_sel:[0,1,0]
	v_pk_fma_f32 v[240:241], v[166:167], v[126:127], v[240:241] op_sel_hi:[1,0,1]
	v_pk_fma_f32 v[242:243], v[166:167], v[126:127], v[242:243] op_sel:[0,1,0]
	v_pk_fma_f32 v[244:245], v[166:167], v[128:129], v[244:245] op_sel_hi:[1,0,1]
	v_pk_fma_f32 v[246:247], v[166:167], v[128:129], v[246:247] op_sel:[0,1,0]
	v_pk_fma_f32 v[248:249], v[166:167], v[130:131], v[248:249] op_sel_hi:[1,0,1]
	v_pk_fma_f32 v[250:251], v[166:167], v[130:131], v[250:251] op_sel:[0,1,0]
	ds_read_b128 v[124:127], v252 offset:2608
	ds_read_b128 v[128:131], v252 offset:2688
	ds_read_b64 v[166:167], v253 offset:512
	s_waitcnt lgkmcnt(10)
	v_pk_mul_f32 v[172:173], v[236:237], v[132:133] op_sel_hi:[1,0]
	v_pk_mul_f32 v[174:175], v[238:239], v[132:133] op_sel:[0,1]
	v_pk_fma_f32 v[172:173], v[240:241], v[134:135], v[172:173] op_sel_hi:[1,0,1]
	v_pk_fma_f32 v[174:175], v[242:243], v[134:135], v[174:175] op_sel:[0,1,0]
	v_pk_fma_f32 v[172:173], v[244:245], v[136:137], v[172:173] op_sel_hi:[1,0,1]
	v_pk_fma_f32 v[174:175], v[246:247], v[136:137], v[174:175] op_sel:[0,1,0]
	v_pk_fma_f32 v[172:173], v[248:249], v[138:139], v[172:173] op_sel_hi:[1,0,1]
	v_pk_fma_f32 v[174:175], v[250:251], v[138:139], v[174:175] op_sel:[0,1,0]
	ds_read_b128 v[132:135], v252 offset:2624
	ds_read_b128 v[136:139], v252 offset:2704
	v_pk_add_f32 v[172:173], v[172:173], v[174:175]
	ds_write_b64 v254, v[172:173] offset:2048
	s_waitcnt lgkmcnt(10)
	v_pk_mul_f32 v[168:169], v[236:237], v[100:101] op_sel_hi:[1,0]
	v_pk_mul_f32 v[170:171], v[238:239], v[100:101] op_sel:[0,1]
	v_pk_fma_f32 v[168:169], v[240:241], v[102:103], v[168:169] op_sel_hi:[1,0,1]
	v_pk_fma_f32 v[170:171], v[242:243], v[102:103], v[170:171] op_sel:[0,1,0]
	v_pk_fma_f32 v[168:169], v[244:245], v[104:105], v[168:169] op_sel_hi:[1,0,1]
	v_pk_fma_f32 v[170:171], v[246:247], v[104:105], v[170:171] op_sel:[0,1,0]
	v_pk_fma_f32 v[168:169], v[248:249], v[106:107], v[168:169] op_sel_hi:[1,0,1]
	v_pk_fma_f32 v[170:171], v[250:251], v[106:107], v[170:171] op_sel:[0,1,0]
	ds_read_b128 v[100:103], v252 offset:3856
	ds_read_b128 v[104:107], v252 offset:3936
	v_pk_add_f32 v[168:169], v[168:169], v[170:171]
	s_waitcnt lgkmcnt(10)
	v_pk_mul_f32 v[236:237], v[236:237], v[108:109] op_sel_hi:[1,0]
	v_pk_mul_f32 v[238:239], v[238:239], v[108:109] op_sel:[0,1]
	v_pk_mul_f32 v[240:241], v[240:241], v[110:111] op_sel_hi:[1,0]
	v_pk_mul_f32 v[242:243], v[242:243], v[110:111] op_sel:[0,1]
	v_pk_mul_f32 v[244:245], v[244:245], v[112:113] op_sel_hi:[1,0]
	v_pk_mul_f32 v[246:247], v[246:247], v[112:113] op_sel:[0,1]
	v_pk_mul_f32 v[248:249], v[248:249], v[114:115] op_sel_hi:[1,0]
	v_pk_mul_f32 v[250:251], v[250:251], v[114:115] op_sel:[0,1]
	v_add_f32_dpp v168, v168, v168 quad_perm:[1,0,3,2] row_mask:0xf bank_mask:0xf bound_ctrl:1
	v_add_f32_dpp v169, v169, v169 quad_perm:[1,0,3,2] row_mask:0xf bank_mask:0xf bound_ctrl:1
	ds_read_b128 v[108:111], v252 offset:3840
	v_add_f32_dpp v168, v168, v168 quad_perm:[2,3,0,1] row_mask:0xf bank_mask:0xf bound_ctrl:1
	v_add_f32_dpp v169, v169, v169 quad_perm:[2,3,0,1] row_mask:0xf bank_mask:0xf bound_ctrl:1
	ds_read_b128 v[112:115], v252 offset:3920
	v_add_f32_dpp v168, v168, v168 row_half_mirror row_mask:0xf bank_mask:0xf bound_ctrl:1
	v_add_f32_dpp v169, v169, v169 row_half_mirror row_mask:0xf bank_mask:0xf bound_ctrl:1
	s_waitcnt lgkmcnt(10)
	v_pk_fma_f32 v[236:237], v[168:169], v[116:117], v[236:237] op_sel_hi:[1,0,1]
	v_pk_fma_f32 v[238:239], v[168:169], v[116:117], v[238:239] op_sel:[0,1,0]
	v_pk_fma_f32 v[240:241], v[168:169], v[118:119], v[240:241] op_sel_hi:[1,0,1]
	v_pk_fma_f32 v[242:243], v[168:169], v[118:119], v[242:243] op_sel:[0,1,0]
	v_pk_fma_f32 v[244:245], v[168:169], v[120:121], v[244:245] op_sel_hi:[1,0,1]
	v_pk_fma_f32 v[246:247], v[168:169], v[120:121], v[246:247] op_sel:[0,1,0]
	v_pk_fma_f32 v[248:249], v[168:169], v[122:123], v[248:249] op_sel_hi:[1,0,1]
	v_pk_fma_f32 v[250:251], v[168:169], v[122:123], v[250:251] op_sel:[0,1,0]
	ds_read_b128 v[116:119], v252 offset:3872
	ds_read_b128 v[120:123], v252 offset:3952
	s_waitcnt lgkmcnt(9)
	v_pk_fma_f32 v[236:237], v[166:167], v[124:125], v[236:237] op_sel_hi:[1,0,1]
	v_pk_fma_f32 v[238:239], v[166:167], v[124:125], v[238:239] op_sel:[0,1,0]
	v_pk_fma_f32 v[240:241], v[166:167], v[126:127], v[240:241] op_sel_hi:[1,0,1]
	v_pk_fma_f32 v[242:243], v[166:167], v[126:127], v[242:243] op_sel:[0,1,0]
	v_pk_fma_f32 v[244:245], v[166:167], v[128:129], v[244:245] op_sel_hi:[1,0,1]
	v_pk_fma_f32 v[246:247], v[166:167], v[128:129], v[246:247] op_sel:[0,1,0]
	v_pk_fma_f32 v[248:249], v[166:167], v[130:131], v[248:249] op_sel_hi:[1,0,1]
	v_pk_fma_f32 v[250:251], v[166:167], v[130:131], v[250:251] op_sel:[0,1,0]
	ds_read_b128 v[124:127], v252 offset:3888
	ds_read_b128 v[128:131], v252 offset:3968
	ds_read_b64 v[166:167], v253 offset:768
	s_waitcnt lgkmcnt(10)
; #define LAS __attribute__((address_space(3)))
; template <int CTRL> __device__ __forceinline__ float dppf(float v) { return __builtin_bit_cast(float, __builtin_amdgcn_update_dpp(0, __builtin_bit_cast(int, v), CTRL, 0xF, 0xF, true)); }
; #define LO2(v) __builtin_shufflevector(v, v, 0, 1)
; #define HI2(v) __builtin_shufflevector(v, v, 2, 3)
; __device__ __forceinline__ void phase_scan(const Args& a, LAS unsigned char* lds) {
;     ...
;                 for (int s = 0; s < TC; ++s) {
;                     const LAS float* o = obase + (s + 1) * 320;
;                     const f32x4 now = *(const LAS f32x4*)(o), noa = *(const LAS f32x4*)(o + 4), nob = *(const LAS f32x4*)(o + 8), nok = *(const LAS f32x4*)(o + 12), norr = *(const LAS f32x4*)(o + 16);
;                     const f32x2 nvv = *(const LAS f32x2*)(vbase + (s + 1) * 64);
;                     const f32x2 p = pkfma_b<1>(C3, HI2(oa), pkfma_b<0>(C2, HI2(oa), pkfma_b<1>(C1, LO2(oa), pkmul_b<0>(C0, LO2(oa)))));
;                     float sa0 = p.x, sa1 = p.y;
;                     sa0 = reduce16(sa0); asm volatile("" : "+v"(sa0)); sa1 = reduce16(sa1);
;                     const f32x2 sap = {sa0, sa1};
;                     C0 = pkfma_b<0>(vv, LO2(ok), pkfma_b<0>(sap, LO2(ob), pkmul_b<0>(C0, LO2(ow))));
;                     C1 = pkfma_b<1>(vv, LO2(ok), pkfma_b<1>(sap, LO2(ob), pkmul_b<1>(C1, LO2(ow))));
;                     C2 = pkfma_b<0>(vv, HI2(ok), pkfma_b<0>(sap, HI2(ob), pkmul_b<0>(C2, HI2(ow))));
;                     C3 = pkfma_b<1>(vv, HI2(ok), pkfma_b<1>(sap, HI2(ob), pkmul_b<1>(C3, HI2(ow))));
;                     const f32x2 q = pkfma_b<1>(C3, HI2(orr), pkfma_b<0>(C2, HI2(orr), pkfma_b<1>(C1, LO2(orr), pkmul_b<0>(C0, LO2(orr)))));
;                     float y0 = q.x, y1 = q.y;
;                     y0 += dppf<0xB1>(y0); y1 += dppf<0xB1>(y1);
;                     *(LAS f32x2*)(yb + ((s * 32 + (r0 >> 1)) * 8 + ((lane >> 1) & 7)) * 2) = (f32x2){y0, y1};
;                     ow = now; oa = noa; ob = nob; ok = nok; orr = norr; vv = nvv;
;                 }
	v_pk_mul_f32 v[172:173], v[236:237], v[132:133] op_sel_hi:[1,0]
	v_pk_mul_f32 v[174:175], v[238:239], v[132:133] op_sel:[0,1]
	v_pk_fma_f32 v[172:173], v[240:241], v[134:135], v[172:173] op_sel_hi:[1,0,1]
	v_pk_fma_f32 v[174:175], v[242:243], v[134:135], v[174:175] op_sel:[0,1,0]
	v_pk_fma_f32 v[172:173], v[244:245], v[136:137], v[172:173] op_sel_hi:[1,0,1]
	v_pk_fma_f32 v[174:175], v[246:247], v[136:137], v[174:175] op_sel:[0,1,0]
	v_pk_fma_f32 v[172:173], v[248:249], v[138:139], v[172:173] op_sel_hi:[1,0,1]
	v_pk_fma_f32 v[174:175], v[250:251], v[138:139], v[174:175] op_sel:[0,1,0]
	ds_read_b128 v[132:135], v252 offset:3904
	ds_read_b128 v[136:139], v252 offset:3984
	v_pk_add_f32 v[172:173], v[172:173], v[174:175]
	ds_write_b64 v254, v[172:173] offset:4096
	s_waitcnt lgkmcnt(10)
	v_pk_mul_f32 v[168:169], v[236:237], v[100:101] op_sel_hi:[1,0]
	v_pk_mul_f32 v[170:171], v[238:239], v[100:101] op_sel:[0,1]
	v_pk_fma_f32 v[168:169], v[240:241], v[102:103], v[168:169] op_sel_hi:[1,0,1]
	v_pk_fma_f32 v[170:171], v[242:243], v[102:103], v[170:171] op_sel:[0,1,0]
	v_pk_fma_f32 v[168:169], v[244:245], v[104:105], v[168:169] op_sel_hi:[1,0,1]
	v_pk_fma_f32 v[170:171], v[246:247], v[104:105], v[170:171] op_sel:[0,1,0]
	v_pk_fma_f32 v[168:169], v[248:249], v[106:107], v[168:169] op_sel_hi:[1,0,1]
	v_pk_fma_f32 v[170:171], v[250:251], v[106:107], v[170:171] op_sel:[0,1,0]
	ds_read_b128 v[100:103], v252 offset:5136
	ds_read_b128 v[104:107], v252 offset:5216
	v_pk_add_f32 v[168:169], v[168:169], v[170:171]
	s_waitcnt lgkmcnt(10)
	v_pk_mul_f32 v[236:237], v[236:237], v[108:109] op_sel_hi:[1,0]
	v_pk_mul_f32 v[238:239], v[238:239], v[108:109] op_sel:[0,1]
	v_pk_mul_f32 v[240:241], v[240:241], v[110:111] op_sel_hi:[1,0]
	v_pk_mul_f32 v[242:243], v[242:243], v[110:111] op_sel:[0,1]
	v_pk_mul_f32 v[244:245], v[244:245], v[112:113] op_sel_hi:[1,0]
	v_pk_mul_f32 v[246:247], v[246:247], v[112:113] op_sel:[0,1]
	v_pk_mul_f32 v[248:249], v[248:249], v[114:115] op_sel_hi:[1,0]
	v_pk_mul_f32 v[250:251], v[250:251], v[114:115] op_sel:[0,1]
	v_add_f32_dpp v168, v168, v168 quad_perm:[1,0,3,2] row_mask:0xf bank_mask:0xf bound_ctrl:1
	v_add_f32_dpp v169, v169, v169 quad_perm:[1,0,3,2] row_mask:0xf bank_mask:0xf bound_ctrl:1
	ds_read_b128 v[108:111], v252 offset:5120
	v_add_f32_dpp v168, v168, v168 quad_perm:[2,3,0,1] row_mask:0xf bank_mask:0xf bound_ctrl:1
	v_add_f32_dpp v169, v169, v169 quad_perm:[2,3,0,1] row_mask:0xf bank_mask:0xf bound_ctrl:1
	ds_read_b128 v[112:115], v252 offset:5200
	v_add_f32_dpp v168, v168, v168 row_half_mirror row_mask:0xf bank_mask:0xf bound_ctrl:1
	v_add_f32_dpp v169, v169, v169 row_half_mirror row_mask:0xf bank_mask:0xf bound_ctrl:1
	s_waitcnt lgkmcnt(10)
	v_pk_fma_f32 v[236:237], v[168:169], v[116:117], v[236:237] op_sel_hi:[1,0,1]
	v_pk_fma_f32 v[238:239], v[168:169], v[116:117], v[238:239] op_sel:[0,1,0]
	v_pk_fma_f32 v[240:241], v[168:169], v[118:119], v[240:241] op_sel_hi:[1,0,1]
	v_pk_fma_f32 v[242:243], v[168:169], v[118:119], v[242:243] op_sel:[0,1,0]
	v_pk_fma_f32 v[244:245], v[168:169], v[120:121], v[244:245] op_sel_hi:[1,0,1]
	v_pk_fma_f32 v[246:247], v[168:169], v[120:121], v[246:247] op_sel:[0,1,0]
	v_pk_fma_f32 v[248:249], v[168:169], v[122:123], v[248:249] op_sel_hi:[1,0,1]
	v_pk_fma_f32 v[250:251], v[168:169], v[122:123], v[250:251] op_sel:[0,1,0]
	ds_read_b128 v[116:119], v252 offset:5152
	ds_read_b128 v[120:123], v252 offset:5232
	s_waitcnt lgkmcnt(9)
	v_pk_fma_f32 v[236:237], v[166:167], v[124:125], v[236:237] op_sel_hi:[1,0,1]
	v_pk_fma_f32 v[238:239], v[166:167], v[124:125], v[238:239] op_sel:[0,1,0]
	v_pk_fma_f32 v[240:241], v[166:167], v[126:127], v[240:241] op_sel_hi:[1,0,1]
	v_pk_fma_f32 v[242:243], v[166:167], v[126:127], v[242:243] op_sel:[0,1,0]
	v_pk_fma_f32 v[244:245], v[166:167], v[128:129], v[244:245] op_sel_hi:[1,0,1]
	v_pk_fma_f32 v[246:247], v[166:167], v[128:129], v[246:247] op_sel:[0,1,0]
	v_pk_fma_f32 v[248:249], v[166:167], v[130:131], v[248:249] op_sel_hi:[1,0,1]
	v_pk_fma_f32 v[250:251], v[166:167], v[130:131], v[250:251] op_sel:[0,1,0]
	ds_read_b128 v[124:127], v252 offset:5168
	ds_read_b128 v[128:131], v252 offset:5248
	ds_read_b64 v[166:167], v253 offset:1024
	s_waitcnt lgkmcnt(10)
	v_pk_mul_f32 v[172:173], v[236:237], v[132:133] op_sel_hi:[1,0]
	v_pk_mul_f32 v[174:175], v[238:239], v[132:133] op_sel:[0,1]
	v_pk_fma_f32 v[172:173], v[240:241], v[134:135], v[172:173] op_sel_hi:[1,0,1]
	v_pk_fma_f32 v[174:175], v[242:243], v[134:135], v[174:175] op_sel:[0,1,0]
	v_pk_fma_f32 v[172:173], v[244:245], v[136:137], v[172:173] op_sel_hi:[1,0,1]
	v_pk_fma_f32 v[174:175], v[246:247], v[136:137], v[174:175] op_sel:[0,1,0]
	v_pk_fma_f32 v[172:173], v[248:249], v[138:139], v[172:173] op_sel_hi:[1,0,1]
	v_pk_fma_f32 v[174:175], v[250:251], v[138:139], v[174:175] op_sel:[0,1,0]
	ds_read_b128 v[132:135], v252 offset:5184
	ds_read_b128 v[136:139], v252 offset:5264
	v_pk_add_f32 v[172:173], v[172:173], v[174:175]
	ds_write_b64 v254, v[172:173] offset:6144
	s_waitcnt lgkmcnt(10)
	v_pk_mul_f32 v[168:169], v[236:237], v[100:101] op_sel_hi:[1,0]
	v_pk_mul_f32 v[170:171], v[238:239], v[100:101] op_sel:[0,1]
	v_pk_fma_f32 v[168:169], v[240:241], v[102:103], v[168:169] op_sel_hi:[1,0,1]
	v_pk_fma_f32 v[170:171], v[242:243], v[102:103], v[170:171] op_sel:[0,1,0]
	v_pk_fma_f32 v[168:169], v[244:245], v[104:105], v[168:169] op_sel_hi:[1,0,1]
	v_pk_fma_f32 v[170:171], v[246:247], v[104:105], v[170:171] op_sel:[0,1,0]
	v_pk_fma_f32 v[168:169], v[248:249], v[106:107], v[168:169] op_sel_hi:[1,0,1]
	v_pk_fma_f32 v[170:171], v[250:251], v[106:107], v[170:171] op_sel:[0,1,0]
	ds_read_b128 v[100:103], v252 offset:6416
	ds_read_b128 v[104:107], v252 offset:6496
	v_pk_add_f32 v[168:169], v[168:169], v[170:171]
	s_waitcnt lgkmcnt(10)
; #define LAS __attribute__((address_space(3)))
; template <int CTRL> __device__ __forceinline__ float dppf(float v) { return __builtin_bit_cast(float, __builtin_amdgcn_update_dpp(0, __builtin_bit_cast(int, v), CTRL, 0xF, 0xF, true)); }
; #define LO2(v) __builtin_shufflevector(v, v, 0, 1)
; #define HI2(v) __builtin_shufflevector(v, v, 2, 3)
; __device__ __forceinline__ void phase_scan(const Args& a, LAS unsigned char* lds) {
;     ...
;                 for (int s = 0; s < TC; ++s) {
;                     const LAS float* o = obase + (s + 1) * 320;
;                     const f32x4 now = *(const LAS f32x4*)(o), noa = *(const LAS f32x4*)(o + 4), nob = *(const LAS f32x4*)(o + 8), nok = *(const LAS f32x4*)(o + 12), norr = *(const LAS f32x4*)(o + 16);
;                     const f32x2 nvv = *(const LAS f32x2*)(vbase + (s + 1) * 64);
;                     const f32x2 p = pkfma_b<1>(C3, HI2(oa), pkfma_b<0>(C2, HI2(oa), pkfma_b<1>(C1, LO2(oa), pkmul_b<0>(C0, LO2(oa)))));
;                     float sa0 = p.x, sa1 = p.y;
;                     sa0 = reduce16(sa0); asm volatile("" : "+v"(sa0)); sa1 = reduce16(sa1);
;                     const f32x2 sap = {sa0, sa1};
;                     C0 = pkfma_b<0>(vv, LO2(ok), pkfma_b<0>(sap, LO2(ob), pkmul_b<0>(C0, LO2(ow))));
;                     C1 = pkfma_b<1>(vv, LO2(ok), pkfma_b<1>(sap, LO2(ob), pkmul_b<1>(C1, LO2(ow))));
;                     C2 = pkfma_b<0>(vv, HI2(ok), pkfma_b<0>(sap, HI2(ob), pkmul_b<0>(C2, HI2(ow))));
;                     C3 = pkfma_b<1>(vv, HI2(ok), pkfma_b<1>(sap, HI2(ob), pkmul_b<1>(C3, HI2(ow))));
;                     const f32x2 q = pkfma_b<1>(C3, HI2(orr), pkfma_b<0>(C2, HI2(orr), pkfma_b<1>(C1, LO2(orr), pkmul_b<0>(C0, LO2(orr)))));
;                     float y0 = q.x, y1 = q.y;
;                     y0 += dppf<0xB1>(y0); y1 += dppf<0xB1>(y1);
;                     *(LAS f32x2*)(yb + ((s * 32 + (r0 >> 1)) * 8 + ((lane >> 1) & 7)) * 2) = (f32x2){y0, y1};
;                     ow = now; oa = noa; ob = nob; ok = nok; orr = norr; vv = nvv;
;                 }
	v_pk_mul_f32 v[236:237], v[236:237], v[108:109] op_sel_hi:[1,0]
	v_pk_mul_f32 v[238:239], v[238:239], v[108:109] op_sel:[0,1]
	v_pk_mul_f32 v[240:241], v[240:241], v[110:111] op_sel_hi:[1,0]
	v_pk_mul_f32 v[242:243], v[242:243], v[110:111] op_sel:[0,1]
	v_pk_mul_f32 v[244:245], v[244:245], v[112:113] op_sel_hi:[1,0]
	v_pk_mul_f32 v[246:247], v[246:247], v[112:113] op_sel:[0,1]
	v_pk_mul_f32 v[248:249], v[248:249], v[114:115] op_sel_hi:[1,0]
	v_pk_mul_f32 v[250:251], v[250:251], v[114:115] op_sel:[0,1]
	v_add_f32_dpp v168, v168, v168 quad_perm:[1,0,3,2] row_mask:0xf bank_mask:0xf bound_ctrl:1
	v_add_f32_dpp v169, v169, v169 quad_perm:[1,0,3,2] row_mask:0xf bank_mask:0xf bound_ctrl:1
	ds_read_b128 v[108:111], v252 offset:6400
	v_add_f32_dpp v168, v168, v168 quad_perm:[2,3,0,1] row_mask:0xf bank_mask:0xf bound_ctrl:1
	v_add_f32_dpp v169, v169, v169 quad_perm:[2,3,0,1] row_mask:0xf bank_mask:0xf bound_ctrl:1
	ds_read_b128 v[112:115], v252 offset:6480
	v_add_f32_dpp v168, v168, v168 row_half_mirror row_mask:0xf bank_mask:0xf bound_ctrl:1
	v_add_f32_dpp v169, v169, v169 row_half_mirror row_mask:0xf bank_mask:0xf bound_ctrl:1
	s_waitcnt lgkmcnt(10)
	v_pk_fma_f32 v[236:237], v[168:169], v[116:117], v[236:237] op_sel_hi:[1,0,1]
	v_pk_fma_f32 v[238:239], v[168:169], v[116:117], v[238:239] op_sel:[0,1,0]
	v_pk_fma_f32 v[240:241], v[168:169], v[118:119], v[240:241] op_sel_hi:[1,0,1]
	v_pk_fma_f32 v[242:243], v[168:169], v[118:119], v[242:243] op_sel:[0,1,0]
	v_pk_fma_f32 v[244:245], v[168:169], v[120:121], v[244:245] op_sel_hi:[1,0,1]
	v_pk_fma_f32 v[246:247], v[168:169], v[120:121], v[246:247] op_sel:[0,1,0]
	v_pk_fma_f32 v[248:249], v[168:169], v[122:123], v[248:249] op_sel_hi:[1,0,1]
	v_pk_fma_f32 v[250:251], v[168:169], v[122:123], v[250:251] op_sel:[0,1,0]
	ds_read_b128 v[116:119], v252 offset:6432
	ds_read_b128 v[120:123], v252 offset:6512
	s_waitcnt lgkmcnt(9)
	v_pk_fma_f32 v[236:237], v[166:167], v[124:125], v[236:237] op_sel_hi:[1,0,1]
	v_pk_fma_f32 v[238:239], v[166:167], v[124:125], v[238:239] op_sel:[0,1,0]
	v_pk_fma_f32 v[240:241], v[166:167], v[126:127], v[240:241] op_sel_hi:[1,0,1]
	v_pk_fma_f32 v[242:243], v[166:167], v[126:127], v[242:243] op_sel:[0,1,0]
	v_pk_fma_f32 v[244:245], v[166:167], v[128:129], v[244:245] op_sel_hi:[1,0,1]
	v_pk_fma_f32 v[246:247], v[166:167], v[128:129], v[246:247] op_sel:[0,1,0]
	v_pk_fma_f32 v[248:249], v[166:167], v[130:131], v[248:249] op_sel_hi:[1,0,1]
	v_pk_fma_f32 v[250:251], v[166:167], v[130:131], v[250:251] op_sel:[0,1,0]
	ds_read_b128 v[124:127], v252 offset:6448
	ds_read_b128 v[128:131], v252 offset:6528
	ds_read_b64 v[166:167], v253 offset:1280
	s_waitcnt lgkmcnt(10)
	v_pk_mul_f32 v[172:173], v[236:237], v[132:133] op_sel_hi:[1,0]
	v_pk_mul_f32 v[174:175], v[238:239], v[132:133] op_sel:[0,1]
	v_pk_fma_f32 v[172:173], v[240:241], v[134:135], v[172:173] op_sel_hi:[1,0,1]
	v_pk_fma_f32 v[174:175], v[242:243], v[134:135], v[174:175] op_sel:[0,1,0]
	v_pk_fma_f32 v[172:173], v[244:245], v[136:137], v[172:173] op_sel_hi:[1,0,1]
	v_pk_fma_f32 v[174:175], v[246:247], v[136:137], v[174:175] op_sel:[0,1,0]
	v_pk_fma_f32 v[172:173], v[248:249], v[138:139], v[172:173] op_sel_hi:[1,0,1]
	v_pk_fma_f32 v[174:175], v[250:251], v[138:139], v[174:175] op_sel:[0,1,0]
	ds_read_b128 v[132:135], v252 offset:6464
	ds_read_b128 v[136:139], v252 offset:6544
	v_pk_add_f32 v[172:173], v[172:173], v[174:175]
	ds_write_b64 v254, v[172:173] offset:8192
	s_waitcnt lgkmcnt(10)
	v_pk_mul_f32 v[168:169], v[236:237], v[100:101] op_sel_hi:[1,0]
	v_pk_mul_f32 v[170:171], v[238:239], v[100:101] op_sel:[0,1]
	v_pk_fma_f32 v[168:169], v[240:241], v[102:103], v[168:169] op_sel_hi:[1,0,1]
	v_pk_fma_f32 v[170:171], v[242:243], v[102:103], v[170:171] op_sel:[0,1,0]
	v_pk_fma_f32 v[168:169], v[244:245], v[104:105], v[168:169] op_sel_hi:[1,0,1]
	v_pk_fma_f32 v[170:171], v[246:247], v[104:105], v[170:171] op_sel:[0,1,0]
	v_pk_fma_f32 v[168:169], v[248:249], v[106:107], v[168:169] op_sel_hi:[1,0,1]
	v_pk_fma_f32 v[170:171], v[250:251], v[106:107], v[170:171] op_sel:[0,1,0]
	ds_read_b128 v[100:103], v252 offset:7696
	ds_read_b128 v[104:107], v252 offset:7776
	v_pk_add_f32 v[168:169], v[168:169], v[170:171]
	s_waitcnt lgkmcnt(10)
	v_pk_mul_f32 v[236:237], v[236:237], v[108:109] op_sel_hi:[1,0]
	v_pk_mul_f32 v[238:239], v[238:239], v[108:109] op_sel:[0,1]
	v_pk_mul_f32 v[240:241], v[240:241], v[110:111] op_sel_hi:[1,0]
	v_pk_mul_f32 v[242:243], v[242:243], v[110:111] op_sel:[0,1]
	v_pk_mul_f32 v[244:245], v[244:245], v[112:113] op_sel_hi:[1,0]
	v_pk_mul_f32 v[246:247], v[246:247], v[112:113] op_sel:[0,1]
	v_pk_mul_f32 v[248:249], v[248:249], v[114:115] op_sel_hi:[1,0]
	v_pk_mul_f32 v[250:251], v[250:251], v[114:115] op_sel:[0,1]
	v_add_f32_dpp v168, v168, v168 quad_perm:[1,0,3,2] row_mask:0xf bank_mask:0xf bound_ctrl:1
	v_add_f32_dpp v169, v169, v169 quad_perm:[1,0,3,2] row_mask:0xf bank_mask:0xf bound_ctrl:1
	ds_read_b128 v[108:111], v252 offset:7680
	v_add_f32_dpp v168, v168, v168 quad_perm:[2,3,0,1] row_mask:0xf bank_mask:0xf bound_ctrl:1
	v_add_f32_dpp v169, v169, v169 quad_perm:[2,3,0,1] row_mask:0xf bank_mask:0xf bound_ctrl:1
	ds_read_b128 v[112:115], v252 offset:7760
	v_add_f32_dpp v168, v168, v168 row_half_mirror row_mask:0xf bank_mask:0xf bound_ctrl:1
	v_add_f32_dpp v169, v169, v169 row_half_mirror row_mask:0xf bank_mask:0xf bound_ctrl:1
	s_waitcnt lgkmcnt(10)
; #define LAS __attribute__((address_space(3)))
; template <int CTRL> __device__ __forceinline__ float dppf(float v) { return __builtin_bit_cast(float, __builtin_amdgcn_update_dpp(0, __builtin_bit_cast(int, v), CTRL, 0xF, 0xF, true)); }
; #define LO2(v) __builtin_shufflevector(v, v, 0, 1)
; #define HI2(v) __builtin_shufflevector(v, v, 2, 3)
; __device__ __forceinline__ void phase_scan(const Args& a, LAS unsigned char* lds) {
;     ...
;                 for (int s = 0; s < TC; ++s) {
;                     const LAS float* o = obase + (s + 1) * 320;
;                     const f32x4 now = *(const LAS f32x4*)(o), noa = *(const LAS f32x4*)(o + 4), nob = *(const LAS f32x4*)(o + 8), nok = *(const LAS f32x4*)(o + 12), norr = *(const LAS f32x4*)(o + 16);
;                     const f32x2 nvv = *(const LAS f32x2*)(vbase + (s + 1) * 64);
;                     const f32x2 p = pkfma_b<1>(C3, HI2(oa), pkfma_b<0>(C2, HI2(oa), pkfma_b<1>(C1, LO2(oa), pkmul_b<0>(C0, LO2(oa)))));
;                     float sa0 = p.x, sa1 = p.y;
;                     sa0 = reduce16(sa0); asm volatile("" : "+v"(sa0)); sa1 = reduce16(sa1);
;                     const f32x2 sap = {sa0, sa1};
;                     C0 = pkfma_b<0>(vv, LO2(ok), pkfma_b<0>(sap, LO2(ob), pkmul_b<0>(C0, LO2(ow))));
;                     C1 = pkfma_b<1>(vv, LO2(ok), pkfma_b<1>(sap, LO2(ob), pkmul_b<1>(C1, LO2(ow))));
;                     C2 = pkfma_b<0>(vv, HI2(ok), pkfma_b<0>(sap, HI2(ob), pkmul_b<0>(C2, HI2(ow))));
;                     C3 = pkfma_b<1>(vv, HI2(ok), pkfma_b<1>(sap, HI2(ob), pkmul_b<1>(C3, HI2(ow))));
;                     const f32x2 q = pkfma_b<1>(C3, HI2(orr), pkfma_b<0>(C2, HI2(orr), pkfma_b<1>(C1, LO2(orr), pkmul_b<0>(C0, LO2(orr)))));
;                     float y0 = q.x, y1 = q.y;
;                     y0 += dppf<0xB1>(y0); y1 += dppf<0xB1>(y1);
;                     *(LAS f32x2*)(yb + ((s * 32 + (r0 >> 1)) * 8 + ((lane >> 1) & 7)) * 2) = (f32x2){y0, y1};
;                     ow = now; oa = noa; ob = nob; ok = nok; orr = norr; vv = nvv;
;                 }
	v_pk_fma_f32 v[236:237], v[168:169], v[116:117], v[236:237] op_sel_hi:[1,0,1]
	v_pk_fma_f32 v[238:239], v[168:169], v[116:117], v[238:239] op_sel:[0,1,0]
	v_pk_fma_f32 v[240:241], v[168:169], v[118:119], v[240:241] op_sel_hi:[1,0,1]
	v_pk_fma_f32 v[242:243], v[168:169], v[118:119], v[242:243] op_sel:[0,1,0]
	v_pk_fma_f32 v[244:245], v[168:169], v[120:121], v[244:245] op_sel_hi:[1,0,1]
	v_pk_fma_f32 v[246:247], v[168:169], v[120:121], v[246:247] op_sel:[0,1,0]
	v_pk_fma_f32 v[248:249], v[168:169], v[122:123], v[248:249] op_sel_hi:[1,0,1]
	v_pk_fma_f32 v[250:251], v[168:169], v[122:123], v[250:251] op_sel:[0,1,0]
	ds_read_b128 v[116:119], v252 offset:7712
	ds_read_b128 v[120:123], v252 offset:7792
	s_waitcnt lgkmcnt(9)
	v_pk_fma_f32 v[236:237], v[166:167], v[124:125], v[236:237] op_sel_hi:[1,0,1]
	v_pk_fma_f32 v[238:239], v[166:167], v[124:125], v[238:239] op_sel:[0,1,0]
	v_pk_fma_f32 v[240:241], v[166:167], v[126:127], v[240:241] op_sel_hi:[1,0,1]
	v_pk_fma_f32 v[242:243], v[166:167], v[126:127], v[242:243] op_sel:[0,1,0]
	v_pk_fma_f32 v[244:245], v[166:167], v[128:129], v[244:245] op_sel_hi:[1,0,1]
	v_pk_fma_f32 v[246:247], v[166:167], v[128:129], v[246:247] op_sel:[0,1,0]
	v_pk_fma_f32 v[248:249], v[166:167], v[130:131], v[248:249] op_sel_hi:[1,0,1]
	v_pk_fma_f32 v[250:251], v[166:167], v[130:131], v[250:251] op_sel:[0,1,0]
	ds_read_b128 v[124:127], v252 offset:7728
	ds_read_b128 v[128:131], v252 offset:7808
	ds_read_b64 v[166:167], v253 offset:1536
	s_waitcnt lgkmcnt(10)
	v_pk_mul_f32 v[172:173], v[236:237], v[132:133] op_sel_hi:[1,0]
	v_pk_mul_f32 v[174:175], v[238:239], v[132:133] op_sel:[0,1]
	v_pk_fma_f32 v[172:173], v[240:241], v[134:135], v[172:173] op_sel_hi:[1,0,1]
	v_pk_fma_f32 v[174:175], v[242:243], v[134:135], v[174:175] op_sel:[0,1,0]
	v_pk_fma_f32 v[172:173], v[244:245], v[136:137], v[172:173] op_sel_hi:[1,0,1]
	v_pk_fma_f32 v[174:175], v[246:247], v[136:137], v[174:175] op_sel:[0,1,0]
	v_pk_fma_f32 v[172:173], v[248:249], v[138:139], v[172:173] op_sel_hi:[1,0,1]
	v_pk_fma_f32 v[174:175], v[250:251], v[138:139], v[174:175] op_sel:[0,1,0]
	ds_read_b128 v[132:135], v252 offset:7744
	ds_read_b128 v[136:139], v252 offset:7824
	v_pk_add_f32 v[172:173], v[172:173], v[174:175]
	ds_write_b64 v254, v[172:173] offset:10240
	s_waitcnt lgkmcnt(10)
	v_pk_mul_f32 v[168:169], v[236:237], v[100:101] op_sel_hi:[1,0]
	v_pk_mul_f32 v[170:171], v[238:239], v[100:101] op_sel:[0,1]
	v_pk_fma_f32 v[168:169], v[240:241], v[102:103], v[168:169] op_sel_hi:[1,0,1]
	v_pk_fma_f32 v[170:171], v[242:243], v[102:103], v[170:171] op_sel:[0,1,0]
	v_pk_fma_f32 v[168:169], v[244:245], v[104:105], v[168:169] op_sel_hi:[1,0,1]
	v_pk_fma_f32 v[170:171], v[246:247], v[104:105], v[170:171] op_sel:[0,1,0]
	v_pk_fma_f32 v[168:169], v[248:249], v[106:107], v[168:169] op_sel_hi:[1,0,1]
	v_pk_fma_f32 v[170:171], v[250:251], v[106:107], v[170:171] op_sel:[0,1,0]
	ds_read_b128 v[100:103], v252 offset:8976
	ds_read_b128 v[104:107], v252 offset:9056
	v_pk_add_f32 v[168:169], v[168:169], v[170:171]
	s_waitcnt lgkmcnt(10)
	v_pk_mul_f32 v[236:237], v[236:237], v[108:109] op_sel_hi:[1,0]
	v_pk_mul_f32 v[238:239], v[238:239], v[108:109] op_sel:[0,1]
	v_pk_mul_f32 v[240:241], v[240:241], v[110:111] op_sel_hi:[1,0]
	v_pk_mul_f32 v[242:243], v[242:243], v[110:111] op_sel:[0,1]
	v_pk_mul_f32 v[244:245], v[244:245], v[112:113] op_sel_hi:[1,0]
	v_pk_mul_f32 v[246:247], v[246:247], v[112:113] op_sel:[0,1]
	v_pk_mul_f32 v[248:249], v[248:249], v[114:115] op_sel_hi:[1,0]
	v_pk_mul_f32 v[250:251], v[250:251], v[114:115] op_sel:[0,1]
	v_add_f32_dpp v168, v168, v168 quad_perm:[1,0,3,2] row_mask:0xf bank_mask:0xf bound_ctrl:1
	v_add_f32_dpp v169, v169, v169 quad_perm:[1,0,3,2] row_mask:0xf bank_mask:0xf bound_ctrl:1
	ds_read_b128 v[108:111], v252 offset:8960
	v_add_f32_dpp v168, v168, v168 quad_perm:[2,3,0,1] row_mask:0xf bank_mask:0xf bound_ctrl:1
	v_add_f32_dpp v169, v169, v169 quad_perm:[2,3,0,1] row_mask:0xf bank_mask:0xf bound_ctrl:1
	ds_read_b128 v[112:115], v252 offset:9040
	v_add_f32_dpp v168, v168, v168 row_half_mirror row_mask:0xf bank_mask:0xf bound_ctrl:1
	v_add_f32_dpp v169, v169, v169 row_half_mirror row_mask:0xf bank_mask:0xf bound_ctrl:1
	s_waitcnt lgkmcnt(10)
	v_pk_fma_f32 v[236:237], v[168:169], v[116:117], v[236:237] op_sel_hi:[1,0,1]
	v_pk_fma_f32 v[238:239], v[168:169], v[116:117], v[238:239] op_sel:[0,1,0]
	v_pk_fma_f32 v[240:241], v[168:169], v[118:119], v[240:241] op_sel_hi:[1,0,1]
	v_pk_fma_f32 v[242:243], v[168:169], v[118:119], v[242:243] op_sel:[0,1,0]
	v_pk_fma_f32 v[244:245], v[168:169], v[120:121], v[244:245] op_sel_hi:[1,0,1]
	v_pk_fma_f32 v[246:247], v[168:169], v[120:121], v[246:247] op_sel:[0,1,0]
	v_pk_fma_f32 v[248:249], v[168:169], v[122:123], v[248:249] op_sel_hi:[1,0,1]
	v_pk_fma_f32 v[250:251], v[168:169], v[122:123], v[250:251] op_sel:[0,1,0]
	ds_read_b128 v[116:119], v252 offset:8992
	ds_read_b128 v[120:123], v252 offset:9072
	s_waitcnt lgkmcnt(9)
	v_pk_fma_f32 v[236:237], v[166:167], v[124:125], v[236:237] op_sel_hi:[1,0,1]
	v_pk_fma_f32 v[238:239], v[166:167], v[124:125], v[238:239] op_sel:[0,1,0]
	v_pk_fma_f32 v[240:241], v[166:167], v[126:127], v[240:241] op_sel_hi:[1,0,1]
	v_pk_fma_f32 v[242:243], v[166:167], v[126:127], v[242:243] op_sel:[0,1,0]
	v_pk_fma_f32 v[244:245], v[166:167], v[128:129], v[244:245] op_sel_hi:[1,0,1]
	v_pk_fma_f32 v[246:247], v[166:167], v[128:129], v[246:247] op_sel:[0,1,0]
	v_pk_fma_f32 v[248:249], v[166:167], v[130:131], v[248:249] op_sel_hi:[1,0,1]
	v_pk_fma_f32 v[250:251], v[166:167], v[130:131], v[250:251] op_sel:[0,1,0]
	ds_read_b128 v[124:127], v252 offset:9008
	ds_read_b128 v[128:131], v252 offset:9088
	ds_read_b64 v[166:167], v253 offset:1792
	s_waitcnt lgkmcnt(10)
; #define LAS __attribute__((address_space(3)))
; template <int CTRL> __device__ __forceinline__ float dppf(float v) { return __builtin_bit_cast(float, __builtin_amdgcn_update_dpp(0, __builtin_bit_cast(int, v), CTRL, 0xF, 0xF, true)); }
; #define LO2(v) __builtin_shufflevector(v, v, 0, 1)
; #define HI2(v) __builtin_shufflevector(v, v, 2, 3)
; __device__ __forceinline__ void phase_scan(const Args& a, LAS unsigned char* lds) {
;     ...
;                 for (int s = 0; s < TC; ++s) {
;                     const LAS float* o = obase + (s + 1) * 320;
;                     const f32x4 now = *(const LAS f32x4*)(o), noa = *(const LAS f32x4*)(o + 4), nob = *(const LAS f32x4*)(o + 8), nok = *(const LAS f32x4*)(o + 12), norr = *(const LAS f32x4*)(o + 16);
;                     const f32x2 nvv = *(const LAS f32x2*)(vbase + (s + 1) * 64);
;                     const f32x2 p = pkfma_b<1>(C3, HI2(oa), pkfma_b<0>(C2, HI2(oa), pkfma_b<1>(C1, LO2(oa), pkmul_b<0>(C0, LO2(oa)))));
;                     float sa0 = p.x, sa1 = p.y;
;                     sa0 = reduce16(sa0); asm volatile("" : "+v"(sa0)); sa1 = reduce16(sa1);
;                     const f32x2 sap = {sa0, sa1};
;                     C0 = pkfma_b<0>(vv, LO2(ok), pkfma_b<0>(sap, LO2(ob), pkmul_b<0>(C0, LO2(ow))));
;                     C1 = pkfma_b<1>(vv, LO2(ok), pkfma_b<1>(sap, LO2(ob), pkmul_b<1>(C1, LO2(ow))));
;                     C2 = pkfma_b<0>(vv, HI2(ok), pkfma_b<0>(sap, HI2(ob), pkmul_b<0>(C2, HI2(ow))));
;                     C3 = pkfma_b<1>(vv, HI2(ok), pkfma_b<1>(sap, HI2(ob), pkmul_b<1>(C3, HI2(ow))));
;                     const f32x2 q = pkfma_b<1>(C3, HI2(orr), pkfma_b<0>(C2, HI2(orr), pkfma_b<1>(C1, LO2(orr), pkmul_b<0>(C0, LO2(orr)))));
;                     float y0 = q.x, y1 = q.y;
;                     y0 += dppf<0xB1>(y0); y1 += dppf<0xB1>(y1);
;                     *(LAS f32x2*)(yb + ((s * 32 + (r0 >> 1)) * 8 + ((lane >> 1) & 7)) * 2) = (f32x2){y0, y1};
;                     ow = now; oa = noa; ob = nob; ok = nok; orr = norr; vv = nvv;
;                 }
	v_pk_mul_f32 v[172:173], v[236:237], v[132:133] op_sel_hi:[1,0]
	v_pk_mul_f32 v[174:175], v[238:239], v[132:133] op_sel:[0,1]
	v_pk_fma_f32 v[172:173], v[240:241], v[134:135], v[172:173] op_sel_hi:[1,0,1]
	v_pk_fma_f32 v[174:175], v[242:243], v[134:135], v[174:175] op_sel:[0,1,0]
	v_pk_fma_f32 v[172:173], v[244:245], v[136:137], v[172:173] op_sel_hi:[1,0,1]
	v_pk_fma_f32 v[174:175], v[246:247], v[136:137], v[174:175] op_sel:[0,1,0]
	v_pk_fma_f32 v[172:173], v[248:249], v[138:139], v[172:173] op_sel_hi:[1,0,1]
	v_pk_fma_f32 v[174:175], v[250:251], v[138:139], v[174:175] op_sel:[0,1,0]
	ds_read_b128 v[132:135], v252 offset:9024
	ds_read_b128 v[136:139], v252 offset:9104
	v_pk_add_f32 v[172:173], v[172:173], v[174:175]
	ds_write_b64 v254, v[172:173] offset:12288
	s_waitcnt lgkmcnt(10)
	v_pk_mul_f32 v[168:169], v[236:237], v[100:101] op_sel_hi:[1,0]
	v_pk_mul_f32 v[170:171], v[238:239], v[100:101] op_sel:[0,1]
	v_pk_fma_f32 v[168:169], v[240:241], v[102:103], v[168:169] op_sel_hi:[1,0,1]
	v_pk_fma_f32 v[170:171], v[242:243], v[102:103], v[170:171] op_sel:[0,1,0]
	v_pk_fma_f32 v[168:169], v[244:245], v[104:105], v[168:169] op_sel_hi:[1,0,1]
	v_pk_fma_f32 v[170:171], v[246:247], v[104:105], v[170:171] op_sel:[0,1,0]
	v_pk_fma_f32 v[168:169], v[248:249], v[106:107], v[168:169] op_sel_hi:[1,0,1]
	v_pk_fma_f32 v[170:171], v[250:251], v[106:107], v[170:171] op_sel:[0,1,0]
	ds_read_b128 v[100:103], v252 offset:10256
	ds_read_b128 v[104:107], v252 offset:10336
	v_pk_add_f32 v[168:169], v[168:169], v[170:171]
	s_waitcnt lgkmcnt(10)
	v_pk_mul_f32 v[236:237], v[236:237], v[108:109] op_sel_hi:[1,0]
	v_pk_mul_f32 v[238:239], v[238:239], v[108:109] op_sel:[0,1]
	v_pk_mul_f32 v[240:241], v[240:241], v[110:111] op_sel_hi:[1,0]
	v_pk_mul_f32 v[242:243], v[242:243], v[110:111] op_sel:[0,1]
	v_pk_mul_f32 v[244:245], v[244:245], v[112:113] op_sel_hi:[1,0]
	v_pk_mul_f32 v[246:247], v[246:247], v[112:113] op_sel:[0,1]
	v_pk_mul_f32 v[248:249], v[248:249], v[114:115] op_sel_hi:[1,0]
	v_pk_mul_f32 v[250:251], v[250:251], v[114:115] op_sel:[0,1]
	v_add_f32_dpp v168, v168, v168 quad_perm:[1,0,3,2] row_mask:0xf bank_mask:0xf bound_ctrl:1
	v_add_f32_dpp v169, v169, v169 quad_perm:[1,0,3,2] row_mask:0xf bank_mask:0xf bound_ctrl:1
	ds_read_b128 v[108:111], v252 offset:10240
	v_add_f32_dpp v168, v168, v168 quad_perm:[2,3,0,1] row_mask:0xf bank_mask:0xf bound_ctrl:1
	v_add_f32_dpp v169, v169, v169 quad_perm:[2,3,0,1] row_mask:0xf bank_mask:0xf bound_ctrl:1
	ds_read_b128 v[112:115], v252 offset:10320
	v_add_f32_dpp v168, v168, v168 row_half_mirror row_mask:0xf bank_mask:0xf bound_ctrl:1
	v_add_f32_dpp v169, v169, v169 row_half_mirror row_mask:0xf bank_mask:0xf bound_ctrl:1
	s_waitcnt lgkmcnt(10)
	v_pk_fma_f32 v[236:237], v[168:169], v[116:117], v[236:237] op_sel_hi:[1,0,1]
	v_pk_fma_f32 v[238:239], v[168:169], v[116:117], v[238:239] op_sel:[0,1,0]
	v_pk_fma_f32 v[240:241], v[168:169], v[118:119], v[240:241] op_sel_hi:[1,0,1]
	v_pk_fma_f32 v[242:243], v[168:169], v[118:119], v[242:243] op_sel:[0,1,0]
	v_pk_fma_f32 v[244:245], v[168:169], v[120:121], v[244:245] op_sel_hi:[1,0,1]
	v_pk_fma_f32 v[246:247], v[168:169], v[120:121], v[246:247] op_sel:[0,1,0]
	v_pk_fma_f32 v[248:249], v[168:169], v[122:123], v[248:249] op_sel_hi:[1,0,1]
	v_pk_fma_f32 v[250:251], v[168:169], v[122:123], v[250:251] op_sel:[0,1,0]
	ds_read_b128 v[116:119], v252 offset:10272
	ds_read_b128 v[120:123], v252 offset:10352
	s_waitcnt lgkmcnt(9)
	v_pk_fma_f32 v[236:237], v[166:167], v[124:125], v[236:237] op_sel_hi:[1,0,1]
	v_pk_fma_f32 v[238:239], v[166:167], v[124:125], v[238:239] op_sel:[0,1,0]
	v_pk_fma_f32 v[240:241], v[166:167], v[126:127], v[240:241] op_sel_hi:[1,0,1]
	v_pk_fma_f32 v[242:243], v[166:167], v[126:127], v[242:243] op_sel:[0,1,0]
	v_pk_fma_f32 v[244:245], v[166:167], v[128:129], v[244:245] op_sel_hi:[1,0,1]
	v_pk_fma_f32 v[246:247], v[166:167], v[128:129], v[246:247] op_sel:[0,1,0]
	v_pk_fma_f32 v[248:249], v[166:167], v[130:131], v[248:249] op_sel_hi:[1,0,1]
	v_pk_fma_f32 v[250:251], v[166:167], v[130:131], v[250:251] op_sel:[0,1,0]
	ds_read_b128 v[124:127], v252 offset:10288
	ds_read_b128 v[128:131], v252 offset:10368
	ds_read_b64 v[166:167], v253 offset:2048
	s_waitcnt lgkmcnt(10)
	v_pk_mul_f32 v[172:173], v[236:237], v[132:133] op_sel_hi:[1,0]
	v_pk_mul_f32 v[174:175], v[238:239], v[132:133] op_sel:[0,1]
	v_pk_fma_f32 v[172:173], v[240:241], v[134:135], v[172:173] op_sel_hi:[1,0,1]
	v_pk_fma_f32 v[174:175], v[242:243], v[134:135], v[174:175] op_sel:[0,1,0]
	v_pk_fma_f32 v[172:173], v[244:245], v[136:137], v[172:173] op_sel_hi:[1,0,1]
	v_pk_fma_f32 v[174:175], v[246:247], v[136:137], v[174:175] op_sel:[0,1,0]
	v_pk_fma_f32 v[172:173], v[248:249], v[138:139], v[172:173] op_sel_hi:[1,0,1]
	v_pk_fma_f32 v[174:175], v[250:251], v[138:139], v[174:175] op_sel:[0,1,0]
	ds_read_b128 v[132:135], v252 offset:10304
	ds_read_b128 v[136:139], v252 offset:10384
	v_pk_add_f32 v[172:173], v[172:173], v[174:175]
	ds_write_b64 v254, v[172:173] offset:14336
	s_waitcnt lgkmcnt(10)
	v_pk_mul_f32 v[168:169], v[236:237], v[100:101] op_sel_hi:[1,0]
	v_pk_mul_f32 v[170:171], v[238:239], v[100:101] op_sel:[0,1]
	v_pk_fma_f32 v[168:169], v[240:241], v[102:103], v[168:169] op_sel_hi:[1,0,1]
	v_pk_fma_f32 v[170:171], v[242:243], v[102:103], v[170:171] op_sel:[0,1,0]
	v_pk_fma_f32 v[168:169], v[244:245], v[104:105], v[168:169] op_sel_hi:[1,0,1]
	v_pk_fma_f32 v[170:171], v[246:247], v[104:105], v[170:171] op_sel:[0,1,0]
	v_pk_fma_f32 v[168:169], v[248:249], v[106:107], v[168:169] op_sel_hi:[1,0,1]
	v_pk_fma_f32 v[170:171], v[250:251], v[106:107], v[170:171] op_sel:[0,1,0]
	ds_read_b128 v[100:103], v252 offset:11536
	ds_read_b128 v[104:107], v252 offset:11616
	v_pk_add_f32 v[168:169], v[168:169], v[170:171]
	s_waitcnt lgkmcnt(10)
; #define LAS __attribute__((address_space(3)))
; template <int CTRL> __device__ __forceinline__ float dppf(float v) { return __builtin_bit_cast(float, __builtin_amdgcn_update_dpp(0, __builtin_bit_cast(int, v), CTRL, 0xF, 0xF, true)); }
; #define LO2(v) __builtin_shufflevector(v, v, 0, 1)
; #define HI2(v) __builtin_shufflevector(v, v, 2, 3)
; __device__ __forceinline__ void phase_scan(const Args& a, LAS unsigned char* lds) {
;     ...
;                 for (int s = 0; s < TC; ++s) {
;                     const LAS float* o = obase + (s + 1) * 320;
;                     const f32x4 now = *(const LAS f32x4*)(o), noa = *(const LAS f32x4*)(o + 4), nob = *(const LAS f32x4*)(o + 8), nok = *(const LAS f32x4*)(o + 12), norr = *(const LAS f32x4*)(o + 16);
;                     const f32x2 nvv = *(const LAS f32x2*)(vbase + (s + 1) * 64);
;                     const f32x2 p = pkfma_b<1>(C3, HI2(oa), pkfma_b<0>(C2, HI2(oa), pkfma_b<1>(C1, LO2(oa), pkmul_b<0>(C0, LO2(oa)))));
;                     float sa0 = p.x, sa1 = p.y;
;                     sa0 = reduce16(sa0); asm volatile("" : "+v"(sa0)); sa1 = reduce16(sa1);
;                     const f32x2 sap = {sa0, sa1};
;                     C0 = pkfma_b<0>(vv, LO2(ok), pkfma_b<0>(sap, LO2(ob), pkmul_b<0>(C0, LO2(ow))));
;                     C1 = pkfma_b<1>(vv, LO2(ok), pkfma_b<1>(sap, LO2(ob), pkmul_b<1>(C1, LO2(ow))));
;                     C2 = pkfma_b<0>(vv, HI2(ok), pkfma_b<0>(sap, HI2(ob), pkmul_b<0>(C2, HI2(ow))));
;                     C3 = pkfma_b<1>(vv, HI2(ok), pkfma_b<1>(sap, HI2(ob), pkmul_b<1>(C3, HI2(ow))));
;                     const f32x2 q = pkfma_b<1>(C3, HI2(orr), pkfma_b<0>(C2, HI2(orr), pkfma_b<1>(C1, LO2(orr), pkmul_b<0>(C0, LO2(orr)))));
;                     float y0 = q.x, y1 = q.y;
;                     y0 += dppf<0xB1>(y0); y1 += dppf<0xB1>(y1);
;                     *(LAS f32x2*)(yb + ((s * 32 + (r0 >> 1)) * 8 + ((lane >> 1) & 7)) * 2) = (f32x2){y0, y1};
;                     ow = now; oa = noa; ob = nob; ok = nok; orr = norr; vv = nvv;
;                 }
	v_pk_mul_f32 v[236:237], v[236:237], v[108:109] op_sel_hi:[1,0]
	v_pk_mul_f32 v[238:239], v[238:239], v[108:109] op_sel:[0,1]
	v_pk_mul_f32 v[240:241], v[240:241], v[110:111] op_sel_hi:[1,0]
	v_pk_mul_f32 v[242:243], v[242:243], v[110:111] op_sel:[0,1]
	v_pk_mul_f32 v[244:245], v[244:245], v[112:113] op_sel_hi:[1,0]
	v_pk_mul_f32 v[246:247], v[246:247], v[112:113] op_sel:[0,1]
	v_pk_mul_f32 v[248:249], v[248:249], v[114:115] op_sel_hi:[1,0]
	v_pk_mul_f32 v[250:251], v[250:251], v[114:115] op_sel:[0,1]
	v_add_f32_dpp v168, v168, v168 quad_perm:[1,0,3,2] row_mask:0xf bank_mask:0xf bound_ctrl:1
	v_add_f32_dpp v169, v169, v169 quad_perm:[1,0,3,2] row_mask:0xf bank_mask:0xf bound_ctrl:1
	ds_read_b128 v[108:111], v252 offset:11520
	v_add_f32_dpp v168, v168, v168 quad_perm:[2,3,0,1] row_mask:0xf bank_mask:0xf bound_ctrl:1
	v_add_f32_dpp v169, v169, v169 quad_perm:[2,3,0,1] row_mask:0xf bank_mask:0xf bound_ctrl:1
	ds_read_b128 v[112:115], v252 offset:11600
	v_add_f32_dpp v168, v168, v168 row_half_mirror row_mask:0xf bank_mask:0xf bound_ctrl:1
	v_add_f32_dpp v169, v169, v169 row_half_mirror row_mask:0xf bank_mask:0xf bound_ctrl:1
	s_waitcnt lgkmcnt(10)
	v_pk_fma_f32 v[236:237], v[168:169], v[116:117], v[236:237] op_sel_hi:[1,0,1]
	v_pk_fma_f32 v[238:239], v[168:169], v[116:117], v[238:239] op_sel:[0,1,0]
	v_pk_fma_f32 v[240:241], v[168:169], v[118:119], v[240:241] op_sel_hi:[1,0,1]
	v_pk_fma_f32 v[242:243], v[168:169], v[118:119], v[242:243] op_sel:[0,1,0]
	v_pk_fma_f32 v[244:245], v[168:169], v[120:121], v[244:245] op_sel_hi:[1,0,1]
	v_pk_fma_f32 v[246:247], v[168:169], v[120:121], v[246:247] op_sel:[0,1,0]
	v_pk_fma_f32 v[248:249], v[168:169], v[122:123], v[248:249] op_sel_hi:[1,0,1]
	v_pk_fma_f32 v[250:251], v[168:169], v[122:123], v[250:251] op_sel:[0,1,0]
	ds_read_b128 v[116:119], v252 offset:11552
	ds_read_b128 v[120:123], v252 offset:11632
	s_waitcnt lgkmcnt(9)
	v_pk_fma_f32 v[236:237], v[166:167], v[124:125], v[236:237] op_sel_hi:[1,0,1]
	v_pk_fma_f32 v[238:239], v[166:167], v[124:125], v[238:239] op_sel:[0,1,0]
	v_pk_fma_f32 v[240:241], v[166:167], v[126:127], v[240:241] op_sel_hi:[1,0,1]
	v_pk_fma_f32 v[242:243], v[166:167], v[126:127], v[242:243] op_sel:[0,1,0]
	v_pk_fma_f32 v[244:245], v[166:167], v[128:129], v[244:245] op_sel_hi:[1,0,1]
	v_pk_fma_f32 v[246:247], v[166:167], v[128:129], v[246:247] op_sel:[0,1,0]
	v_pk_fma_f32 v[248:249], v[166:167], v[130:131], v[248:249] op_sel_hi:[1,0,1]
	v_pk_fma_f32 v[250:251], v[166:167], v[130:131], v[250:251] op_sel:[0,1,0]
	ds_read_b128 v[124:127], v252 offset:11568
	ds_read_b128 v[128:131], v252 offset:11648
	ds_read_b64 v[166:167], v253 offset:2304
	s_waitcnt lgkmcnt(10)
	v_pk_mul_f32 v[172:173], v[236:237], v[132:133] op_sel_hi:[1,0]
	v_pk_mul_f32 v[174:175], v[238:239], v[132:133] op_sel:[0,1]
	v_pk_fma_f32 v[172:173], v[240:241], v[134:135], v[172:173] op_sel_hi:[1,0,1]
	v_pk_fma_f32 v[174:175], v[242:243], v[134:135], v[174:175] op_sel:[0,1,0]
	v_pk_fma_f32 v[172:173], v[244:245], v[136:137], v[172:173] op_sel_hi:[1,0,1]
	v_pk_fma_f32 v[174:175], v[246:247], v[136:137], v[174:175] op_sel:[0,1,0]
	v_pk_fma_f32 v[172:173], v[248:249], v[138:139], v[172:173] op_sel_hi:[1,0,1]
	v_pk_fma_f32 v[174:175], v[250:251], v[138:139], v[174:175] op_sel:[0,1,0]
	ds_read_b128 v[132:135], v252 offset:11584
	ds_read_b128 v[136:139], v252 offset:11664
	v_pk_add_f32 v[172:173], v[172:173], v[174:175]
	ds_write_b64 v254, v[172:173] offset:16384
	s_waitcnt lgkmcnt(10)
	v_pk_mul_f32 v[168:169], v[236:237], v[100:101] op_sel_hi:[1,0]
	v_pk_mul_f32 v[170:171], v[238:239], v[100:101] op_sel:[0,1]
	v_pk_fma_f32 v[168:169], v[240:241], v[102:103], v[168:169] op_sel_hi:[1,0,1]
	v_pk_fma_f32 v[170:171], v[242:243], v[102:103], v[170:171] op_sel:[0,1,0]
	v_pk_fma_f32 v[168:169], v[244:245], v[104:105], v[168:169] op_sel_hi:[1,0,1]
	v_pk_fma_f32 v[170:171], v[246:247], v[104:105], v[170:171] op_sel:[0,1,0]
	v_pk_fma_f32 v[168:169], v[248:249], v[106:107], v[168:169] op_sel_hi:[1,0,1]
	v_pk_fma_f32 v[170:171], v[250:251], v[106:107], v[170:171] op_sel:[0,1,0]
	ds_read_b128 v[100:103], v252 offset:12816
	ds_read_b128 v[104:107], v252 offset:12896
	v_pk_add_f32 v[168:169], v[168:169], v[170:171]
	s_waitcnt lgkmcnt(10)
	v_pk_mul_f32 v[236:237], v[236:237], v[108:109] op_sel_hi:[1,0]
	v_pk_mul_f32 v[238:239], v[238:239], v[108:109] op_sel:[0,1]
	v_pk_mul_f32 v[240:241], v[240:241], v[110:111] op_sel_hi:[1,0]
	v_pk_mul_f32 v[242:243], v[242:243], v[110:111] op_sel:[0,1]
	v_pk_mul_f32 v[244:245], v[244:245], v[112:113] op_sel_hi:[1,0]
	v_pk_mul_f32 v[246:247], v[246:247], v[112:113] op_sel:[0,1]
	v_pk_mul_f32 v[248:249], v[248:249], v[114:115] op_sel_hi:[1,0]
	v_pk_mul_f32 v[250:251], v[250:251], v[114:115] op_sel:[0,1]
	v_add_f32_dpp v168, v168, v168 quad_perm:[1,0,3,2] row_mask:0xf bank_mask:0xf bound_ctrl:1
	v_add_f32_dpp v169, v169, v169 quad_perm:[1,0,3,2] row_mask:0xf bank_mask:0xf bound_ctrl:1
	ds_read_b128 v[108:111], v252 offset:12800
	v_add_f32_dpp v168, v168, v168 quad_perm:[2,3,0,1] row_mask:0xf bank_mask:0xf bound_ctrl:1
	v_add_f32_dpp v169, v169, v169 quad_perm:[2,3,0,1] row_mask:0xf bank_mask:0xf bound_ctrl:1
	ds_read_b128 v[112:115], v252 offset:12880
	v_add_f32_dpp v168, v168, v168 row_half_mirror row_mask:0xf bank_mask:0xf bound_ctrl:1
	v_add_f32_dpp v169, v169, v169 row_half_mirror row_mask:0xf bank_mask:0xf bound_ctrl:1
	s_waitcnt lgkmcnt(10)
; #define LAS __attribute__((address_space(3)))
; template <int CTRL> __device__ __forceinline__ float dppf(float v) { return __builtin_bit_cast(float, __builtin_amdgcn_update_dpp(0, __builtin_bit_cast(int, v), CTRL, 0xF, 0xF, true)); }
; #define LO2(v) __builtin_shufflevector(v, v, 0, 1)
; #define HI2(v) __builtin_shufflevector(v, v, 2, 3)
; __device__ __forceinline__ void phase_scan(const Args& a, LAS unsigned char* lds) {
;     ...
;                 for (int s = 0; s < TC; ++s) {
;                     const LAS float* o = obase + (s + 1) * 320;
;                     const f32x4 now = *(const LAS f32x4*)(o), noa = *(const LAS f32x4*)(o + 4), nob = *(const LAS f32x4*)(o + 8), nok = *(const LAS f32x4*)(o + 12), norr = *(const LAS f32x4*)(o + 16);
;                     const f32x2 nvv = *(const LAS f32x2*)(vbase + (s + 1) * 64);
;                     const f32x2 p = pkfma_b<1>(C3, HI2(oa), pkfma_b<0>(C2, HI2(oa), pkfma_b<1>(C1, LO2(oa), pkmul_b<0>(C0, LO2(oa)))));
;                     float sa0 = p.x, sa1 = p.y;
;                     sa0 = reduce16(sa0); asm volatile("" : "+v"(sa0)); sa1 = reduce16(sa1);
;                     const f32x2 sap = {sa0, sa1};
;                     C0 = pkfma_b<0>(vv, LO2(ok), pkfma_b<0>(sap, LO2(ob), pkmul_b<0>(C0, LO2(ow))));
;                     C1 = pkfma_b<1>(vv, LO2(ok), pkfma_b<1>(sap, LO2(ob), pkmul_b<1>(C1, LO2(ow))));
;                     C2 = pkfma_b<0>(vv, HI2(ok), pkfma_b<0>(sap, HI2(ob), pkmul_b<0>(C2, HI2(ow))));
;                     C3 = pkfma_b<1>(vv, HI2(ok), pkfma_b<1>(sap, HI2(ob), pkmul_b<1>(C3, HI2(ow))));
;                     const f32x2 q = pkfma_b<1>(C3, HI2(orr), pkfma_b<0>(C2, HI2(orr), pkfma_b<1>(C1, LO2(orr), pkmul_b<0>(C0, LO2(orr)))));
;                     float y0 = q.x, y1 = q.y;
;                     y0 += dppf<0xB1>(y0); y1 += dppf<0xB1>(y1);
;                     *(LAS f32x2*)(yb + ((s * 32 + (r0 >> 1)) * 8 + ((lane >> 1) & 7)) * 2) = (f32x2){y0, y1};
;                     ow = now; oa = noa; ob = nob; ok = nok; orr = norr; vv = nvv;
;                 }
	v_pk_fma_f32 v[236:237], v[168:169], v[116:117], v[236:237] op_sel_hi:[1,0,1]
	v_pk_fma_f32 v[238:239], v[168:169], v[116:117], v[238:239] op_sel:[0,1,0]
	v_pk_fma_f32 v[240:241], v[168:169], v[118:119], v[240:241] op_sel_hi:[1,0,1]
	v_pk_fma_f32 v[242:243], v[168:169], v[118:119], v[242:243] op_sel:[0,1,0]
	v_pk_fma_f32 v[244:245], v[168:169], v[120:121], v[244:245] op_sel_hi:[1,0,1]
	v_pk_fma_f32 v[246:247], v[168:169], v[120:121], v[246:247] op_sel:[0,1,0]
	v_pk_fma_f32 v[248:249], v[168:169], v[122:123], v[248:249] op_sel_hi:[1,0,1]
	v_pk_fma_f32 v[250:251], v[168:169], v[122:123], v[250:251] op_sel:[0,1,0]
	ds_read_b128 v[116:119], v252 offset:12832
	ds_read_b128 v[120:123], v252 offset:12912
	s_waitcnt lgkmcnt(9)
	v_pk_fma_f32 v[236:237], v[166:167], v[124:125], v[236:237] op_sel_hi:[1,0,1]
	v_pk_fma_f32 v[238:239], v[166:167], v[124:125], v[238:239] op_sel:[0,1,0]
	v_pk_fma_f32 v[240:241], v[166:167], v[126:127], v[240:241] op_sel_hi:[1,0,1]
	v_pk_fma_f32 v[242:243], v[166:167], v[126:127], v[242:243] op_sel:[0,1,0]
	v_pk_fma_f32 v[244:245], v[166:167], v[128:129], v[244:245] op_sel_hi:[1,0,1]
	v_pk_fma_f32 v[246:247], v[166:167], v[128:129], v[246:247] op_sel:[0,1,0]
	v_pk_fma_f32 v[248:249], v[166:167], v[130:131], v[248:249] op_sel_hi:[1,0,1]
	v_pk_fma_f32 v[250:251], v[166:167], v[130:131], v[250:251] op_sel:[0,1,0]
	ds_read_b128 v[124:127], v252 offset:12848
	ds_read_b128 v[128:131], v252 offset:12928
	ds_read_b64 v[166:167], v253 offset:2560
	s_waitcnt lgkmcnt(10)
	v_pk_mul_f32 v[172:173], v[236:237], v[132:133] op_sel_hi:[1,0]
	v_pk_mul_f32 v[174:175], v[238:239], v[132:133] op_sel:[0,1]
	v_pk_fma_f32 v[172:173], v[240:241], v[134:135], v[172:173] op_sel_hi:[1,0,1]
	v_pk_fma_f32 v[174:175], v[242:243], v[134:135], v[174:175] op_sel:[0,1,0]
	v_pk_fma_f32 v[172:173], v[244:245], v[136:137], v[172:173] op_sel_hi:[1,0,1]
	v_pk_fma_f32 v[174:175], v[246:247], v[136:137], v[174:175] op_sel:[0,1,0]
	v_pk_fma_f32 v[172:173], v[248:249], v[138:139], v[172:173] op_sel_hi:[1,0,1]
	v_pk_fma_f32 v[174:175], v[250:251], v[138:139], v[174:175] op_sel:[0,1,0]
	ds_read_b128 v[132:135], v252 offset:12864
	ds_read_b128 v[136:139], v252 offset:12944
	v_pk_add_f32 v[172:173], v[172:173], v[174:175]
	ds_write_b64 v254, v[172:173] offset:18432
	s_waitcnt lgkmcnt(10)
	v_pk_mul_f32 v[168:169], v[236:237], v[100:101] op_sel_hi:[1,0]
	v_pk_mul_f32 v[170:171], v[238:239], v[100:101] op_sel:[0,1]
	v_pk_fma_f32 v[168:169], v[240:241], v[102:103], v[168:169] op_sel_hi:[1,0,1]
	v_pk_fma_f32 v[170:171], v[242:243], v[102:103], v[170:171] op_sel:[0,1,0]
	v_pk_fma_f32 v[168:169], v[244:245], v[104:105], v[168:169] op_sel_hi:[1,0,1]
	v_pk_fma_f32 v[170:171], v[246:247], v[104:105], v[170:171] op_sel:[0,1,0]
	v_pk_fma_f32 v[168:169], v[248:249], v[106:107], v[168:169] op_sel_hi:[1,0,1]
	v_pk_fma_f32 v[170:171], v[250:251], v[106:107], v[170:171] op_sel:[0,1,0]
	ds_read_b128 v[100:103], v252 offset:14096
	ds_read_b128 v[104:107], v252 offset:14176
	v_pk_add_f32 v[168:169], v[168:169], v[170:171]
	s_waitcnt lgkmcnt(10)
	v_pk_mul_f32 v[236:237], v[236:237], v[108:109] op_sel_hi:[1,0]
	v_pk_mul_f32 v[238:239], v[238:239], v[108:109] op_sel:[0,1]
	v_pk_mul_f32 v[240:241], v[240:241], v[110:111] op_sel_hi:[1,0]
	v_pk_mul_f32 v[242:243], v[242:243], v[110:111] op_sel:[0,1]
	v_pk_mul_f32 v[244:245], v[244:245], v[112:113] op_sel_hi:[1,0]
	v_pk_mul_f32 v[246:247], v[246:247], v[112:113] op_sel:[0,1]
	v_pk_mul_f32 v[248:249], v[248:249], v[114:115] op_sel_hi:[1,0]
	v_pk_mul_f32 v[250:251], v[250:251], v[114:115] op_sel:[0,1]
	v_add_f32_dpp v168, v168, v168 quad_perm:[1,0,3,2] row_mask:0xf bank_mask:0xf bound_ctrl:1
	v_add_f32_dpp v169, v169, v169 quad_perm:[1,0,3,2] row_mask:0xf bank_mask:0xf bound_ctrl:1
	ds_read_b128 v[108:111], v252 offset:14080
	v_add_f32_dpp v168, v168, v168 quad_perm:[2,3,0,1] row_mask:0xf bank_mask:0xf bound_ctrl:1
	v_add_f32_dpp v169, v169, v169 quad_perm:[2,3,0,1] row_mask:0xf bank_mask:0xf bound_ctrl:1
	ds_read_b128 v[112:115], v252 offset:14160
	v_add_f32_dpp v168, v168, v168 row_half_mirror row_mask:0xf bank_mask:0xf bound_ctrl:1
	v_add_f32_dpp v169, v169, v169 row_half_mirror row_mask:0xf bank_mask:0xf bound_ctrl:1
	s_waitcnt lgkmcnt(10)
	v_pk_fma_f32 v[236:237], v[168:169], v[116:117], v[236:237] op_sel_hi:[1,0,1]
	v_pk_fma_f32 v[238:239], v[168:169], v[116:117], v[238:239] op_sel:[0,1,0]
	v_pk_fma_f32 v[240:241], v[168:169], v[118:119], v[240:241] op_sel_hi:[1,0,1]
	v_pk_fma_f32 v[242:243], v[168:169], v[118:119], v[242:243] op_sel:[0,1,0]
	v_pk_fma_f32 v[244:245], v[168:169], v[120:121], v[244:245] op_sel_hi:[1,0,1]
	v_pk_fma_f32 v[246:247], v[168:169], v[120:121], v[246:247] op_sel:[0,1,0]
	v_pk_fma_f32 v[248:249], v[168:169], v[122:123], v[248:249] op_sel_hi:[1,0,1]
	v_pk_fma_f32 v[250:251], v[168:169], v[122:123], v[250:251] op_sel:[0,1,0]
	ds_read_b128 v[116:119], v252 offset:14112
	ds_read_b128 v[120:123], v252 offset:14192
	s_waitcnt lgkmcnt(9)
	v_pk_fma_f32 v[236:237], v[166:167], v[124:125], v[236:237] op_sel_hi:[1,0,1]
	v_pk_fma_f32 v[238:239], v[166:167], v[124:125], v[238:239] op_sel:[0,1,0]
	v_pk_fma_f32 v[240:241], v[166:167], v[126:127], v[240:241] op_sel_hi:[1,0,1]
	v_pk_fma_f32 v[242:243], v[166:167], v[126:127], v[242:243] op_sel:[0,1,0]
	v_pk_fma_f32 v[244:245], v[166:167], v[128:129], v[244:245] op_sel_hi:[1,0,1]
	v_pk_fma_f32 v[246:247], v[166:167], v[128:129], v[246:247] op_sel:[0,1,0]
	v_pk_fma_f32 v[248:249], v[166:167], v[130:131], v[248:249] op_sel_hi:[1,0,1]
	v_pk_fma_f32 v[250:251], v[166:167], v[130:131], v[250:251] op_sel:[0,1,0]
	ds_read_b128 v[124:127], v252 offset:14128
	ds_read_b128 v[128:131], v252 offset:14208
	ds_read_b64 v[166:167], v253 offset:2816
	s_waitcnt lgkmcnt(10)
; #define LAS __attribute__((address_space(3)))
; template <int CTRL> __device__ __forceinline__ float dppf(float v) { return __builtin_bit_cast(float, __builtin_amdgcn_update_dpp(0, __builtin_bit_cast(int, v), CTRL, 0xF, 0xF, true)); }
; #define LO2(v) __builtin_shufflevector(v, v, 0, 1)
; #define HI2(v) __builtin_shufflevector(v, v, 2, 3)
; __device__ __forceinline__ void phase_scan(const Args& a, LAS unsigned char* lds) {
;     ...
;                 for (int s = 0; s < TC; ++s) {
;                     const LAS float* o = obase + (s + 1) * 320;
;                     const f32x4 now = *(const LAS f32x4*)(o), noa = *(const LAS f32x4*)(o + 4), nob = *(const LAS f32x4*)(o + 8), nok = *(const LAS f32x4*)(o + 12), norr = *(const LAS f32x4*)(o + 16);
;                     const f32x2 nvv = *(const LAS f32x2*)(vbase + (s + 1) * 64);
;                     const f32x2 p = pkfma_b<1>(C3, HI2(oa), pkfma_b<0>(C2, HI2(oa), pkfma_b<1>(C1, LO2(oa), pkmul_b<0>(C0, LO2(oa)))));
;                     float sa0 = p.x, sa1 = p.y;
;                     sa0 = reduce16(sa0); asm volatile("" : "+v"(sa0)); sa1 = reduce16(sa1);
;                     const f32x2 sap = {sa0, sa1};
;                     C0 = pkfma_b<0>(vv, LO2(ok), pkfma_b<0>(sap, LO2(ob), pkmul_b<0>(C0, LO2(ow))));
;                     C1 = pkfma_b<1>(vv, LO2(ok), pkfma_b<1>(sap, LO2(ob), pkmul_b<1>(C1, LO2(ow))));
;                     C2 = pkfma_b<0>(vv, HI2(ok), pkfma_b<0>(sap, HI2(ob), pkmul_b<0>(C2, HI2(ow))));
;                     C3 = pkfma_b<1>(vv, HI2(ok), pkfma_b<1>(sap, HI2(ob), pkmul_b<1>(C3, HI2(ow))));
;                     const f32x2 q = pkfma_b<1>(C3, HI2(orr), pkfma_b<0>(C2, HI2(orr), pkfma_b<1>(C1, LO2(orr), pkmul_b<0>(C0, LO2(orr)))));
;                     float y0 = q.x, y1 = q.y;
;                     y0 += dppf<0xB1>(y0); y1 += dppf<0xB1>(y1);
;                     *(LAS f32x2*)(yb + ((s * 32 + (r0 >> 1)) * 8 + ((lane >> 1) & 7)) * 2) = (f32x2){y0, y1};
;                     ow = now; oa = noa; ob = nob; ok = nok; orr = norr; vv = nvv;
;                 }
	v_pk_mul_f32 v[172:173], v[236:237], v[132:133] op_sel_hi:[1,0]
	v_pk_mul_f32 v[174:175], v[238:239], v[132:133] op_sel:[0,1]
	v_pk_fma_f32 v[172:173], v[240:241], v[134:135], v[172:173] op_sel_hi:[1,0,1]
	v_pk_fma_f32 v[174:175], v[242:243], v[134:135], v[174:175] op_sel:[0,1,0]
	v_pk_fma_f32 v[172:173], v[244:245], v[136:137], v[172:173] op_sel_hi:[1,0,1]
	v_pk_fma_f32 v[174:175], v[246:247], v[136:137], v[174:175] op_sel:[0,1,0]
	v_pk_fma_f32 v[172:173], v[248:249], v[138:139], v[172:173] op_sel_hi:[1,0,1]
	v_pk_fma_f32 v[174:175], v[250:251], v[138:139], v[174:175] op_sel:[0,1,0]
	ds_read_b128 v[132:135], v252 offset:14144
	ds_read_b128 v[136:139], v252 offset:14224
	v_pk_add_f32 v[172:173], v[172:173], v[174:175]
	ds_write_b64 v254, v[172:173] offset:20480
	s_waitcnt lgkmcnt(10)
	v_pk_mul_f32 v[168:169], v[236:237], v[100:101] op_sel_hi:[1,0]
	v_pk_mul_f32 v[170:171], v[238:239], v[100:101] op_sel:[0,1]
	v_pk_fma_f32 v[168:169], v[240:241], v[102:103], v[168:169] op_sel_hi:[1,0,1]
	v_pk_fma_f32 v[170:171], v[242:243], v[102:103], v[170:171] op_sel:[0,1,0]
	v_pk_fma_f32 v[168:169], v[244:245], v[104:105], v[168:169] op_sel_hi:[1,0,1]
	v_pk_fma_f32 v[170:171], v[246:247], v[104:105], v[170:171] op_sel:[0,1,0]
	v_pk_fma_f32 v[168:169], v[248:249], v[106:107], v[168:169] op_sel_hi:[1,0,1]
	v_pk_fma_f32 v[170:171], v[250:251], v[106:107], v[170:171] op_sel:[0,1,0]
	ds_read_b128 v[100:103], v252 offset:15376
	ds_read_b128 v[104:107], v252 offset:15456
	v_pk_add_f32 v[168:169], v[168:169], v[170:171]
	s_waitcnt lgkmcnt(10)
	v_pk_mul_f32 v[236:237], v[236:237], v[108:109] op_sel_hi:[1,0]
	v_pk_mul_f32 v[238:239], v[238:239], v[108:109] op_sel:[0,1]
	v_pk_mul_f32 v[240:241], v[240:241], v[110:111] op_sel_hi:[1,0]
	v_pk_mul_f32 v[242:243], v[242:243], v[110:111] op_sel:[0,1]
	v_pk_mul_f32 v[244:245], v[244:245], v[112:113] op_sel_hi:[1,0]
	v_pk_mul_f32 v[246:247], v[246:247], v[112:113] op_sel:[0,1]
	v_pk_mul_f32 v[248:249], v[248:249], v[114:115] op_sel_hi:[1,0]
	v_pk_mul_f32 v[250:251], v[250:251], v[114:115] op_sel:[0,1]
	v_add_f32_dpp v168, v168, v168 quad_perm:[1,0,3,2] row_mask:0xf bank_mask:0xf bound_ctrl:1
	v_add_f32_dpp v169, v169, v169 quad_perm:[1,0,3,2] row_mask:0xf bank_mask:0xf bound_ctrl:1
	ds_read_b128 v[108:111], v252 offset:15360
	v_add_f32_dpp v168, v168, v168 quad_perm:[2,3,0,1] row_mask:0xf bank_mask:0xf bound_ctrl:1
	v_add_f32_dpp v169, v169, v169 quad_perm:[2,3,0,1] row_mask:0xf bank_mask:0xf bound_ctrl:1
	ds_read_b128 v[112:115], v252 offset:15440
	v_add_f32_dpp v168, v168, v168 row_half_mirror row_mask:0xf bank_mask:0xf bound_ctrl:1
	v_add_f32_dpp v169, v169, v169 row_half_mirror row_mask:0xf bank_mask:0xf bound_ctrl:1
	s_waitcnt lgkmcnt(10)
	v_pk_fma_f32 v[236:237], v[168:169], v[116:117], v[236:237] op_sel_hi:[1,0,1]
	v_pk_fma_f32 v[238:239], v[168:169], v[116:117], v[238:239] op_sel:[0,1,0]
	v_pk_fma_f32 v[240:241], v[168:169], v[118:119], v[240:241] op_sel_hi:[1,0,1]
	v_pk_fma_f32 v[242:243], v[168:169], v[118:119], v[242:243] op_sel:[0,1,0]
	v_pk_fma_f32 v[244:245], v[168:169], v[120:121], v[244:245] op_sel_hi:[1,0,1]
	v_pk_fma_f32 v[246:247], v[168:169], v[120:121], v[246:247] op_sel:[0,1,0]
	v_pk_fma_f32 v[248:249], v[168:169], v[122:123], v[248:249] op_sel_hi:[1,0,1]
	v_pk_fma_f32 v[250:251], v[168:169], v[122:123], v[250:251] op_sel:[0,1,0]
	ds_read_b128 v[116:119], v252 offset:15392
	ds_read_b128 v[120:123], v252 offset:15472
	s_waitcnt lgkmcnt(9)
	v_pk_fma_f32 v[236:237], v[166:167], v[124:125], v[236:237] op_sel_hi:[1,0,1]
	v_pk_fma_f32 v[238:239], v[166:167], v[124:125], v[238:239] op_sel:[0,1,0]
	v_pk_fma_f32 v[240:241], v[166:167], v[126:127], v[240:241] op_sel_hi:[1,0,1]
	v_pk_fma_f32 v[242:243], v[166:167], v[126:127], v[242:243] op_sel:[0,1,0]
	v_pk_fma_f32 v[244:245], v[166:167], v[128:129], v[244:245] op_sel_hi:[1,0,1]
	v_pk_fma_f32 v[246:247], v[166:167], v[128:129], v[246:247] op_sel:[0,1,0]
	v_pk_fma_f32 v[248:249], v[166:167], v[130:131], v[248:249] op_sel_hi:[1,0,1]
	v_pk_fma_f32 v[250:251], v[166:167], v[130:131], v[250:251] op_sel:[0,1,0]
	ds_read_b128 v[124:127], v252 offset:15408
	ds_read_b128 v[128:131], v252 offset:15488
	ds_read_b64 v[166:167], v253 offset:3072
	s_waitcnt lgkmcnt(10)
	v_pk_mul_f32 v[172:173], v[236:237], v[132:133] op_sel_hi:[1,0]
	v_pk_mul_f32 v[174:175], v[238:239], v[132:133] op_sel:[0,1]
	v_pk_fma_f32 v[172:173], v[240:241], v[134:135], v[172:173] op_sel_hi:[1,0,1]
	v_pk_fma_f32 v[174:175], v[242:243], v[134:135], v[174:175] op_sel:[0,1,0]
	v_pk_fma_f32 v[172:173], v[244:245], v[136:137], v[172:173] op_sel_hi:[1,0,1]
	v_pk_fma_f32 v[174:175], v[246:247], v[136:137], v[174:175] op_sel:[0,1,0]
	v_pk_fma_f32 v[172:173], v[248:249], v[138:139], v[172:173] op_sel_hi:[1,0,1]
	v_pk_fma_f32 v[174:175], v[250:251], v[138:139], v[174:175] op_sel:[0,1,0]
	ds_read_b128 v[132:135], v252 offset:15424
	ds_read_b128 v[136:139], v252 offset:15504
	v_pk_add_f32 v[172:173], v[172:173], v[174:175]
	ds_write_b64 v254, v[172:173] offset:22528
	s_barrier
; #define LAS __attribute__((address_space(3)))
; template <int CTRL> __device__ __forceinline__ float dppf(float v) { return __builtin_bit_cast(float, __builtin_amdgcn_update_dpp(0, __builtin_bit_cast(int, v), CTRL, 0xF, 0xF, true)); }
; #define LO2(v) __builtin_shufflevector(v, v, 0, 1)
; #define HI2(v) __builtin_shufflevector(v, v, 2, 3)
; __device__ __forceinline__ void phase_scan(const Args& a, LAS unsigned char* lds) {
;     ...
;                 for (int s = 0; s < TC; ++s) {
;                     const LAS float* o = obase + (s + 1) * 320;
;                     const f32x4 now = *(const LAS f32x4*)(o), noa = *(const LAS f32x4*)(o + 4), nob = *(const LAS f32x4*)(o + 8), nok = *(const LAS f32x4*)(o + 12), norr = *(const LAS f32x4*)(o + 16);
;                     const f32x2 nvv = *(const LAS f32x2*)(vbase + (s + 1) * 64);
;                     const f32x2 p = pkfma_b<1>(C3, HI2(oa), pkfma_b<0>(C2, HI2(oa), pkfma_b<1>(C1, LO2(oa), pkmul_b<0>(C0, LO2(oa)))));
;                     float sa0 = p.x, sa1 = p.y;
;                     sa0 = reduce16(sa0); asm volatile("" : "+v"(sa0)); sa1 = reduce16(sa1);
;                     const f32x2 sap = {sa0, sa1};
;                     C0 = pkfma_b<0>(vv, LO2(ok), pkfma_b<0>(sap, LO2(ob), pkmul_b<0>(C0, LO2(ow))));
;                     C1 = pkfma_b<1>(vv, LO2(ok), pkfma_b<1>(sap, LO2(ob), pkmul_b<1>(C1, LO2(ow))));
;                     C2 = pkfma_b<0>(vv, HI2(ok), pkfma_b<0>(sap, HI2(ob), pkmul_b<0>(C2, HI2(ow))));
;                     C3 = pkfma_b<1>(vv, HI2(ok), pkfma_b<1>(sap, HI2(ob), pkmul_b<1>(C3, HI2(ow))));
;                     const f32x2 q = pkfma_b<1>(C3, HI2(orr), pkfma_b<0>(C2, HI2(orr), pkfma_b<1>(C1, LO2(orr), pkmul_b<0>(C0, LO2(orr)))));
;                     float y0 = q.x, y1 = q.y;
;                     y0 += dppf<0xB1>(y0); y1 += dppf<0xB1>(y1);
;                     *(LAS f32x2*)(yb + ((s * 32 + (r0 >> 1)) * 8 + ((lane >> 1) & 7)) * 2) = (f32x2){y0, y1};
;                     ow = now; oa = noa; ob = nob; ok = nok; orr = norr; vv = nvv;
;                 }
	s_waitcnt lgkmcnt(10)
	v_pk_mul_f32 v[168:169], v[236:237], v[100:101] op_sel_hi:[1,0]
	v_pk_mul_f32 v[170:171], v[238:239], v[100:101] op_sel:[0,1]
	v_pk_fma_f32 v[168:169], v[240:241], v[102:103], v[168:169] op_sel_hi:[1,0,1]
	v_pk_fma_f32 v[170:171], v[242:243], v[102:103], v[170:171] op_sel:[0,1,0]
	v_pk_fma_f32 v[168:169], v[244:245], v[104:105], v[168:169] op_sel_hi:[1,0,1]
	v_pk_fma_f32 v[170:171], v[246:247], v[104:105], v[170:171] op_sel:[0,1,0]
	v_pk_fma_f32 v[168:169], v[248:249], v[106:107], v[168:169] op_sel_hi:[1,0,1]
	v_pk_fma_f32 v[170:171], v[250:251], v[106:107], v[170:171] op_sel:[0,1,0]
	ds_read_b128 v[100:103], v252 offset:16656
	ds_read_b128 v[104:107], v252 offset:16736
	v_pk_add_f32 v[168:169], v[168:169], v[170:171]
	s_waitcnt lgkmcnt(10)
	v_pk_mul_f32 v[236:237], v[236:237], v[108:109] op_sel_hi:[1,0]
	v_pk_mul_f32 v[238:239], v[238:239], v[108:109] op_sel:[0,1]
	v_pk_mul_f32 v[240:241], v[240:241], v[110:111] op_sel_hi:[1,0]
	v_pk_mul_f32 v[242:243], v[242:243], v[110:111] op_sel:[0,1]
	v_pk_mul_f32 v[244:245], v[244:245], v[112:113] op_sel_hi:[1,0]
	v_pk_mul_f32 v[246:247], v[246:247], v[112:113] op_sel:[0,1]
	v_pk_mul_f32 v[248:249], v[248:249], v[114:115] op_sel_hi:[1,0]
	v_pk_mul_f32 v[250:251], v[250:251], v[114:115] op_sel:[0,1]
	v_add_f32_dpp v168, v168, v168 quad_perm:[1,0,3,2] row_mask:0xf bank_mask:0xf bound_ctrl:1
	v_add_f32_dpp v169, v169, v169 quad_perm:[1,0,3,2] row_mask:0xf bank_mask:0xf bound_ctrl:1
	ds_read_b128 v[108:111], v252 offset:16640
	v_add_f32_dpp v168, v168, v168 quad_perm:[2,3,0,1] row_mask:0xf bank_mask:0xf bound_ctrl:1
	v_add_f32_dpp v169, v169, v169 quad_perm:[2,3,0,1] row_mask:0xf bank_mask:0xf bound_ctrl:1
	ds_read_b128 v[112:115], v252 offset:16720
	v_add_f32_dpp v168, v168, v168 row_half_mirror row_mask:0xf bank_mask:0xf bound_ctrl:1
	v_add_f32_dpp v169, v169, v169 row_half_mirror row_mask:0xf bank_mask:0xf bound_ctrl:1
	s_waitcnt lgkmcnt(10)
	v_pk_fma_f32 v[236:237], v[168:169], v[116:117], v[236:237] op_sel_hi:[1,0,1]
	v_pk_fma_f32 v[238:239], v[168:169], v[116:117], v[238:239] op_sel:[0,1,0]
	v_pk_fma_f32 v[240:241], v[168:169], v[118:119], v[240:241] op_sel_hi:[1,0,1]
	v_pk_fma_f32 v[242:243], v[168:169], v[118:119], v[242:243] op_sel:[0,1,0]
	v_pk_fma_f32 v[244:245], v[168:169], v[120:121], v[244:245] op_sel_hi:[1,0,1]
	v_pk_fma_f32 v[246:247], v[168:169], v[120:121], v[246:247] op_sel:[0,1,0]
	v_pk_fma_f32 v[248:249], v[168:169], v[122:123], v[248:249] op_sel_hi:[1,0,1]
	v_pk_fma_f32 v[250:251], v[168:169], v[122:123], v[250:251] op_sel:[0,1,0]
	ds_read_b128 v[116:119], v252 offset:16672
	ds_read_b128 v[120:123], v252 offset:16752
	s_waitcnt lgkmcnt(9)
	v_pk_fma_f32 v[236:237], v[166:167], v[124:125], v[236:237] op_sel_hi:[1,0,1]
	v_pk_fma_f32 v[238:239], v[166:167], v[124:125], v[238:239] op_sel:[0,1,0]
	v_pk_fma_f32 v[240:241], v[166:167], v[126:127], v[240:241] op_sel_hi:[1,0,1]
	v_pk_fma_f32 v[242:243], v[166:167], v[126:127], v[242:243] op_sel:[0,1,0]
	v_pk_fma_f32 v[244:245], v[166:167], v[128:129], v[244:245] op_sel_hi:[1,0,1]
	v_pk_fma_f32 v[246:247], v[166:167], v[128:129], v[246:247] op_sel:[0,1,0]
	v_pk_fma_f32 v[248:249], v[166:167], v[130:131], v[248:249] op_sel_hi:[1,0,1]
	v_pk_fma_f32 v[250:251], v[166:167], v[130:131], v[250:251] op_sel:[0,1,0]
	ds_read_b128 v[124:127], v252 offset:16688
	ds_read_b128 v[128:131], v252 offset:16768
	ds_read_b64 v[166:167], v253 offset:3328
	s_waitcnt lgkmcnt(10)
	v_pk_mul_f32 v[172:173], v[236:237], v[132:133] op_sel_hi:[1,0]
	v_pk_mul_f32 v[174:175], v[238:239], v[132:133] op_sel:[0,1]
	v_pk_fma_f32 v[172:173], v[240:241], v[134:135], v[172:173] op_sel_hi:[1,0,1]
	v_pk_fma_f32 v[174:175], v[242:243], v[134:135], v[174:175] op_sel:[0,1,0]
	v_pk_fma_f32 v[172:173], v[244:245], v[136:137], v[172:173] op_sel_hi:[1,0,1]
	v_pk_fma_f32 v[174:175], v[246:247], v[136:137], v[174:175] op_sel:[0,1,0]
	v_pk_fma_f32 v[172:173], v[248:249], v[138:139], v[172:173] op_sel_hi:[1,0,1]
	v_pk_fma_f32 v[174:175], v[250:251], v[138:139], v[174:175] op_sel:[0,1,0]
	ds_read_b128 v[132:135], v252 offset:16704
	ds_read_b128 v[136:139], v252 offset:16784
	v_pk_add_f32 v[172:173], v[172:173], v[174:175]
	ds_write_b64 v254, v[172:173] offset:24576
	s_waitcnt lgkmcnt(10)
	v_pk_mul_f32 v[168:169], v[236:237], v[100:101] op_sel_hi:[1,0]
	v_pk_mul_f32 v[170:171], v[238:239], v[100:101] op_sel:[0,1]
	v_pk_fma_f32 v[168:169], v[240:241], v[102:103], v[168:169] op_sel_hi:[1,0,1]
	v_pk_fma_f32 v[170:171], v[242:243], v[102:103], v[170:171] op_sel:[0,1,0]
	v_pk_fma_f32 v[168:169], v[244:245], v[104:105], v[168:169] op_sel_hi:[1,0,1]
	v_pk_fma_f32 v[170:171], v[246:247], v[104:105], v[170:171] op_sel:[0,1,0]
	v_pk_fma_f32 v[168:169], v[248:249], v[106:107], v[168:169] op_sel_hi:[1,0,1]
	v_pk_fma_f32 v[170:171], v[250:251], v[106:107], v[170:171] op_sel:[0,1,0]
	ds_read_b128 v[100:103], v252 offset:17936
	ds_read_b128 v[104:107], v252 offset:18016
	v_pk_add_f32 v[168:169], v[168:169], v[170:171]
	s_waitcnt lgkmcnt(10)
	v_pk_mul_f32 v[236:237], v[236:237], v[108:109] op_sel_hi:[1,0]
	v_pk_mul_f32 v[238:239], v[238:239], v[108:109] op_sel:[0,1]
	v_pk_mul_f32 v[240:241], v[240:241], v[110:111] op_sel_hi:[1,0]
	v_pk_mul_f32 v[242:243], v[242:243], v[110:111] op_sel:[0,1]
	v_pk_mul_f32 v[244:245], v[244:245], v[112:113] op_sel_hi:[1,0]
	v_pk_mul_f32 v[246:247], v[246:247], v[112:113] op_sel:[0,1]
	v_pk_mul_f32 v[248:249], v[248:249], v[114:115] op_sel_hi:[1,0]
	v_pk_mul_f32 v[250:251], v[250:251], v[114:115] op_sel:[0,1]
	v_add_f32_dpp v168, v168, v168 quad_perm:[1,0,3,2] row_mask:0xf bank_mask:0xf bound_ctrl:1
	v_add_f32_dpp v169, v169, v169 quad_perm:[1,0,3,2] row_mask:0xf bank_mask:0xf bound_ctrl:1
	ds_read_b128 v[108:111], v252 offset:17920
	v_add_f32_dpp v168, v168, v168 quad_perm:[2,3,0,1] row_mask:0xf bank_mask:0xf bound_ctrl:1
	v_add_f32_dpp v169, v169, v169 quad_perm:[2,3,0,1] row_mask:0xf bank_mask:0xf bound_ctrl:1
	ds_read_b128 v[112:115], v252 offset:18000
	v_add_f32_dpp v168, v168, v168 row_half_mirror row_mask:0xf bank_mask:0xf bound_ctrl:1
	v_add_f32_dpp v169, v169, v169 row_half_mirror row_mask:0xf bank_mask:0xf bound_ctrl:1
	s_waitcnt lgkmcnt(10)
; #define LAS __attribute__((address_space(3)))
; template <int CTRL> __device__ __forceinline__ float dppf(float v) { return __builtin_bit_cast(float, __builtin_amdgcn_update_dpp(0, __builtin_bit_cast(int, v), CTRL, 0xF, 0xF, true)); }
; #define LO2(v) __builtin_shufflevector(v, v, 0, 1)
; #define HI2(v) __builtin_shufflevector(v, v, 2, 3)
; __device__ __forceinline__ void phase_scan(const Args& a, LAS unsigned char* lds) {
;     ...
;                 for (int s = 0; s < TC; ++s) {
;                     const LAS float* o = obase + (s + 1) * 320;
;                     const f32x4 now = *(const LAS f32x4*)(o), noa = *(const LAS f32x4*)(o + 4), nob = *(const LAS f32x4*)(o + 8), nok = *(const LAS f32x4*)(o + 12), norr = *(const LAS f32x4*)(o + 16);
;                     const f32x2 nvv = *(const LAS f32x2*)(vbase + (s + 1) * 64);
;                     const f32x2 p = pkfma_b<1>(C3, HI2(oa), pkfma_b<0>(C2, HI2(oa), pkfma_b<1>(C1, LO2(oa), pkmul_b<0>(C0, LO2(oa)))));
;                     float sa0 = p.x, sa1 = p.y;
;                     sa0 = reduce16(sa0); asm volatile("" : "+v"(sa0)); sa1 = reduce16(sa1);
;                     const f32x2 sap = {sa0, sa1};
;                     C0 = pkfma_b<0>(vv, LO2(ok), pkfma_b<0>(sap, LO2(ob), pkmul_b<0>(C0, LO2(ow))));
;                     C1 = pkfma_b<1>(vv, LO2(ok), pkfma_b<1>(sap, LO2(ob), pkmul_b<1>(C1, LO2(ow))));
;                     C2 = pkfma_b<0>(vv, HI2(ok), pkfma_b<0>(sap, HI2(ob), pkmul_b<0>(C2, HI2(ow))));
;                     C3 = pkfma_b<1>(vv, HI2(ok), pkfma_b<1>(sap, HI2(ob), pkmul_b<1>(C3, HI2(ow))));
;                     const f32x2 q = pkfma_b<1>(C3, HI2(orr), pkfma_b<0>(C2, HI2(orr), pkfma_b<1>(C1, LO2(orr), pkmul_b<0>(C0, LO2(orr)))));
;                     float y0 = q.x, y1 = q.y;
;                     y0 += dppf<0xB1>(y0); y1 += dppf<0xB1>(y1);
;                     *(LAS f32x2*)(yb + ((s * 32 + (r0 >> 1)) * 8 + ((lane >> 1) & 7)) * 2) = (f32x2){y0, y1};
;                     ow = now; oa = noa; ob = nob; ok = nok; orr = norr; vv = nvv;
;                 }
	v_pk_fma_f32 v[236:237], v[168:169], v[116:117], v[236:237] op_sel_hi:[1,0,1]
	v_pk_fma_f32 v[238:239], v[168:169], v[116:117], v[238:239] op_sel:[0,1,0]
	v_pk_fma_f32 v[240:241], v[168:169], v[118:119], v[240:241] op_sel_hi:[1,0,1]
	v_pk_fma_f32 v[242:243], v[168:169], v[118:119], v[242:243] op_sel:[0,1,0]
	v_pk_fma_f32 v[244:245], v[168:169], v[120:121], v[244:245] op_sel_hi:[1,0,1]
	v_pk_fma_f32 v[246:247], v[168:169], v[120:121], v[246:247] op_sel:[0,1,0]
	v_pk_fma_f32 v[248:249], v[168:169], v[122:123], v[248:249] op_sel_hi:[1,0,1]
	v_pk_fma_f32 v[250:251], v[168:169], v[122:123], v[250:251] op_sel:[0,1,0]
	ds_read_b128 v[116:119], v252 offset:17952
	ds_read_b128 v[120:123], v252 offset:18032
	s_waitcnt lgkmcnt(9)
	v_pk_fma_f32 v[236:237], v[166:167], v[124:125], v[236:237] op_sel_hi:[1,0,1]
	v_pk_fma_f32 v[238:239], v[166:167], v[124:125], v[238:239] op_sel:[0,1,0]
	v_pk_fma_f32 v[240:241], v[166:167], v[126:127], v[240:241] op_sel_hi:[1,0,1]
	v_pk_fma_f32 v[242:243], v[166:167], v[126:127], v[242:243] op_sel:[0,1,0]
	v_pk_fma_f32 v[244:245], v[166:167], v[128:129], v[244:245] op_sel_hi:[1,0,1]
	v_pk_fma_f32 v[246:247], v[166:167], v[128:129], v[246:247] op_sel:[0,1,0]
	v_pk_fma_f32 v[248:249], v[166:167], v[130:131], v[248:249] op_sel_hi:[1,0,1]
	v_pk_fma_f32 v[250:251], v[166:167], v[130:131], v[250:251] op_sel:[0,1,0]
	ds_read_b128 v[124:127], v252 offset:17968
	ds_read_b128 v[128:131], v252 offset:18048
	ds_read_b64 v[166:167], v253 offset:3584
	s_waitcnt lgkmcnt(10)
	v_pk_mul_f32 v[172:173], v[236:237], v[132:133] op_sel_hi:[1,0]
	v_pk_mul_f32 v[174:175], v[238:239], v[132:133] op_sel:[0,1]
	v_pk_fma_f32 v[172:173], v[240:241], v[134:135], v[172:173] op_sel_hi:[1,0,1]
	v_pk_fma_f32 v[174:175], v[242:243], v[134:135], v[174:175] op_sel:[0,1,0]
	v_pk_fma_f32 v[172:173], v[244:245], v[136:137], v[172:173] op_sel_hi:[1,0,1]
	v_pk_fma_f32 v[174:175], v[246:247], v[136:137], v[174:175] op_sel:[0,1,0]
	v_pk_fma_f32 v[172:173], v[248:249], v[138:139], v[172:173] op_sel_hi:[1,0,1]
	v_pk_fma_f32 v[174:175], v[250:251], v[138:139], v[174:175] op_sel:[0,1,0]
	ds_read_b128 v[132:135], v252 offset:17984
	ds_read_b128 v[136:139], v252 offset:18064
	v_pk_add_f32 v[172:173], v[172:173], v[174:175]
	ds_write_b64 v254, v[172:173] offset:26624
	s_waitcnt lgkmcnt(10)
	v_pk_mul_f32 v[168:169], v[236:237], v[100:101] op_sel_hi:[1,0]
	v_pk_mul_f32 v[170:171], v[238:239], v[100:101] op_sel:[0,1]
	v_pk_fma_f32 v[168:169], v[240:241], v[102:103], v[168:169] op_sel_hi:[1,0,1]
	v_pk_fma_f32 v[170:171], v[242:243], v[102:103], v[170:171] op_sel:[0,1,0]
	v_pk_fma_f32 v[168:169], v[244:245], v[104:105], v[168:169] op_sel_hi:[1,0,1]
	v_pk_fma_f32 v[170:171], v[246:247], v[104:105], v[170:171] op_sel:[0,1,0]
	v_pk_fma_f32 v[168:169], v[248:249], v[106:107], v[168:169] op_sel_hi:[1,0,1]
	v_pk_fma_f32 v[170:171], v[250:251], v[106:107], v[170:171] op_sel:[0,1,0]
	ds_read_b128 v[100:103], v252 offset:19216
	ds_read_b128 v[104:107], v252 offset:19296
	v_pk_add_f32 v[168:169], v[168:169], v[170:171]
	s_waitcnt lgkmcnt(10)
	v_pk_mul_f32 v[236:237], v[236:237], v[108:109] op_sel_hi:[1,0]
	v_pk_mul_f32 v[238:239], v[238:239], v[108:109] op_sel:[0,1]
	v_pk_mul_f32 v[240:241], v[240:241], v[110:111] op_sel_hi:[1,0]
	v_pk_mul_f32 v[242:243], v[242:243], v[110:111] op_sel:[0,1]
	v_pk_mul_f32 v[244:245], v[244:245], v[112:113] op_sel_hi:[1,0]
	v_pk_mul_f32 v[246:247], v[246:247], v[112:113] op_sel:[0,1]
	v_pk_mul_f32 v[248:249], v[248:249], v[114:115] op_sel_hi:[1,0]
	v_pk_mul_f32 v[250:251], v[250:251], v[114:115] op_sel:[0,1]
	v_add_f32_dpp v168, v168, v168 quad_perm:[1,0,3,2] row_mask:0xf bank_mask:0xf bound_ctrl:1
	v_add_f32_dpp v169, v169, v169 quad_perm:[1,0,3,2] row_mask:0xf bank_mask:0xf bound_ctrl:1
	ds_read_b128 v[108:111], v252 offset:19200
	v_add_f32_dpp v168, v168, v168 quad_perm:[2,3,0,1] row_mask:0xf bank_mask:0xf bound_ctrl:1
	v_add_f32_dpp v169, v169, v169 quad_perm:[2,3,0,1] row_mask:0xf bank_mask:0xf bound_ctrl:1
	ds_read_b128 v[112:115], v252 offset:19280
	v_add_f32_dpp v168, v168, v168 row_half_mirror row_mask:0xf bank_mask:0xf bound_ctrl:1
	v_add_f32_dpp v169, v169, v169 row_half_mirror row_mask:0xf bank_mask:0xf bound_ctrl:1
	s_waitcnt lgkmcnt(10)
	v_pk_fma_f32 v[236:237], v[168:169], v[116:117], v[236:237] op_sel_hi:[1,0,1]
	v_pk_fma_f32 v[238:239], v[168:169], v[116:117], v[238:239] op_sel:[0,1,0]
	v_pk_fma_f32 v[240:241], v[168:169], v[118:119], v[240:241] op_sel_hi:[1,0,1]
	v_pk_fma_f32 v[242:243], v[168:169], v[118:119], v[242:243] op_sel:[0,1,0]
	v_pk_fma_f32 v[244:245], v[168:169], v[120:121], v[244:245] op_sel_hi:[1,0,1]
	v_pk_fma_f32 v[246:247], v[168:169], v[120:121], v[246:247] op_sel:[0,1,0]
	v_pk_fma_f32 v[248:249], v[168:169], v[122:123], v[248:249] op_sel_hi:[1,0,1]
	v_pk_fma_f32 v[250:251], v[168:169], v[122:123], v[250:251] op_sel:[0,1,0]
	ds_read_b128 v[116:119], v252 offset:19232
	ds_read_b128 v[120:123], v252 offset:19312
	s_waitcnt lgkmcnt(9)
	v_pk_fma_f32 v[236:237], v[166:167], v[124:125], v[236:237] op_sel_hi:[1,0,1]
	v_pk_fma_f32 v[238:239], v[166:167], v[124:125], v[238:239] op_sel:[0,1,0]
	v_pk_fma_f32 v[240:241], v[166:167], v[126:127], v[240:241] op_sel_hi:[1,0,1]
	v_pk_fma_f32 v[242:243], v[166:167], v[126:127], v[242:243] op_sel:[0,1,0]
	v_pk_fma_f32 v[244:245], v[166:167], v[128:129], v[244:245] op_sel_hi:[1,0,1]
	v_pk_fma_f32 v[246:247], v[166:167], v[128:129], v[246:247] op_sel:[0,1,0]
	v_pk_fma_f32 v[248:249], v[166:167], v[130:131], v[248:249] op_sel_hi:[1,0,1]
	v_pk_fma_f32 v[250:251], v[166:167], v[130:131], v[250:251] op_sel:[0,1,0]
	ds_read_b128 v[124:127], v252 offset:19248
	ds_read_b128 v[128:131], v252 offset:19328
	ds_read_b64 v[166:167], v253 offset:3840
	s_waitcnt lgkmcnt(10)
; #define LAS __attribute__((address_space(3)))
; template <int CTRL> __device__ __forceinline__ float dppf(float v) { return __builtin_bit_cast(float, __builtin_amdgcn_update_dpp(0, __builtin_bit_cast(int, v), CTRL, 0xF, 0xF, true)); }
; #define LO2(v) __builtin_shufflevector(v, v, 0, 1)
; #define HI2(v) __builtin_shufflevector(v, v, 2, 3)
; __device__ __forceinline__ void phase_scan(const Args& a, LAS unsigned char* lds) {
;     ...
;                 for (int s = 0; s < TC; ++s) {
;                     const LAS float* o = obase + (s + 1) * 320;
;                     const f32x4 now = *(const LAS f32x4*)(o), noa = *(const LAS f32x4*)(o + 4), nob = *(const LAS f32x4*)(o + 8), nok = *(const LAS f32x4*)(o + 12), norr = *(const LAS f32x4*)(o + 16);
;                     const f32x2 nvv = *(const LAS f32x2*)(vbase + (s + 1) * 64);
;                     const f32x2 p = pkfma_b<1>(C3, HI2(oa), pkfma_b<0>(C2, HI2(oa), pkfma_b<1>(C1, LO2(oa), pkmul_b<0>(C0, LO2(oa)))));
;                     float sa0 = p.x, sa1 = p.y;
;                     sa0 = reduce16(sa0); asm volatile("" : "+v"(sa0)); sa1 = reduce16(sa1);
;                     const f32x2 sap = {sa0, sa1};
;                     C0 = pkfma_b<0>(vv, LO2(ok), pkfma_b<0>(sap, LO2(ob), pkmul_b<0>(C0, LO2(ow))));
;                     C1 = pkfma_b<1>(vv, LO2(ok), pkfma_b<1>(sap, LO2(ob), pkmul_b<1>(C1, LO2(ow))));
;                     C2 = pkfma_b<0>(vv, HI2(ok), pkfma_b<0>(sap, HI2(ob), pkmul_b<0>(C2, HI2(ow))));
;                     C3 = pkfma_b<1>(vv, HI2(ok), pkfma_b<1>(sap, HI2(ob), pkmul_b<1>(C3, HI2(ow))));
;                     const f32x2 q = pkfma_b<1>(C3, HI2(orr), pkfma_b<0>(C2, HI2(orr), pkfma_b<1>(C1, LO2(orr), pkmul_b<0>(C0, LO2(orr)))));
;                     float y0 = q.x, y1 = q.y;
;                     y0 += dppf<0xB1>(y0); y1 += dppf<0xB1>(y1);
;                     *(LAS f32x2*)(yb + ((s * 32 + (r0 >> 1)) * 8 + ((lane >> 1) & 7)) * 2) = (f32x2){y0, y1};
;                     ow = now; oa = noa; ob = nob; ok = nok; orr = norr; vv = nvv;
;                 }
	v_pk_mul_f32 v[172:173], v[236:237], v[132:133] op_sel_hi:[1,0]
	v_pk_mul_f32 v[174:175], v[238:239], v[132:133] op_sel:[0,1]
	v_pk_fma_f32 v[172:173], v[240:241], v[134:135], v[172:173] op_sel_hi:[1,0,1]
	v_pk_fma_f32 v[174:175], v[242:243], v[134:135], v[174:175] op_sel:[0,1,0]
	v_pk_fma_f32 v[172:173], v[244:245], v[136:137], v[172:173] op_sel_hi:[1,0,1]
	v_pk_fma_f32 v[174:175], v[246:247], v[136:137], v[174:175] op_sel:[0,1,0]
	v_pk_fma_f32 v[172:173], v[248:249], v[138:139], v[172:173] op_sel_hi:[1,0,1]
	v_pk_fma_f32 v[174:175], v[250:251], v[138:139], v[174:175] op_sel:[0,1,0]
	ds_read_b128 v[132:135], v252 offset:19264
	ds_read_b128 v[136:139], v252 offset:19344
	v_pk_add_f32 v[172:173], v[172:173], v[174:175]
	ds_write_b64 v254, v[172:173] offset:28672
	s_waitcnt lgkmcnt(10)
	v_pk_mul_f32 v[168:169], v[236:237], v[100:101] op_sel_hi:[1,0]
	v_pk_mul_f32 v[170:171], v[238:239], v[100:101] op_sel:[0,1]
	v_pk_fma_f32 v[168:169], v[240:241], v[102:103], v[168:169] op_sel_hi:[1,0,1]
	v_pk_fma_f32 v[170:171], v[242:243], v[102:103], v[170:171] op_sel:[0,1,0]
	v_pk_fma_f32 v[168:169], v[244:245], v[104:105], v[168:169] op_sel_hi:[1,0,1]
	v_pk_fma_f32 v[170:171], v[246:247], v[104:105], v[170:171] op_sel:[0,1,0]
	v_pk_fma_f32 v[168:169], v[248:249], v[106:107], v[168:169] op_sel_hi:[1,0,1]
	v_pk_fma_f32 v[170:171], v[250:251], v[106:107], v[170:171] op_sel:[0,1,0]
	ds_read_b128 v[100:103], v176 offset:16
	ds_read_b128 v[104:107], v176 offset:96
	v_pk_add_f32 v[168:169], v[168:169], v[170:171]
	s_waitcnt lgkmcnt(10)
	v_pk_mul_f32 v[236:237], v[236:237], v[108:109] op_sel_hi:[1,0]
	v_pk_mul_f32 v[238:239], v[238:239], v[108:109] op_sel:[0,1]
	v_pk_mul_f32 v[240:241], v[240:241], v[110:111] op_sel_hi:[1,0]
	v_pk_mul_f32 v[242:243], v[242:243], v[110:111] op_sel:[0,1]
	v_pk_mul_f32 v[244:245], v[244:245], v[112:113] op_sel_hi:[1,0]
	v_pk_mul_f32 v[246:247], v[246:247], v[112:113] op_sel:[0,1]
	v_pk_mul_f32 v[248:249], v[248:249], v[114:115] op_sel_hi:[1,0]
	v_pk_mul_f32 v[250:251], v[250:251], v[114:115] op_sel:[0,1]
	v_add_f32_dpp v168, v168, v168 quad_perm:[1,0,3,2] row_mask:0xf bank_mask:0xf bound_ctrl:1
	v_add_f32_dpp v169, v169, v169 quad_perm:[1,0,3,2] row_mask:0xf bank_mask:0xf bound_ctrl:1
	ds_read_b128 v[108:111], v176
	v_add_f32_dpp v168, v168, v168 quad_perm:[2,3,0,1] row_mask:0xf bank_mask:0xf bound_ctrl:1
	v_add_f32_dpp v169, v169, v169 quad_perm:[2,3,0,1] row_mask:0xf bank_mask:0xf bound_ctrl:1
	ds_read_b128 v[112:115], v176 offset:80
	v_add_f32_dpp v168, v168, v168 row_half_mirror row_mask:0xf bank_mask:0xf bound_ctrl:1
	v_add_f32_dpp v169, v169, v169 row_half_mirror row_mask:0xf bank_mask:0xf bound_ctrl:1
	s_waitcnt lgkmcnt(10)
	v_pk_fma_f32 v[236:237], v[168:169], v[116:117], v[236:237] op_sel_hi:[1,0,1]
	v_pk_fma_f32 v[238:239], v[168:169], v[116:117], v[238:239] op_sel:[0,1,0]
	v_pk_fma_f32 v[240:241], v[168:169], v[118:119], v[240:241] op_sel_hi:[1,0,1]
	v_pk_fma_f32 v[242:243], v[168:169], v[118:119], v[242:243] op_sel:[0,1,0]
	v_pk_fma_f32 v[244:245], v[168:169], v[120:121], v[244:245] op_sel_hi:[1,0,1]
	v_pk_fma_f32 v[246:247], v[168:169], v[120:121], v[246:247] op_sel:[0,1,0]
	v_pk_fma_f32 v[248:249], v[168:169], v[122:123], v[248:249] op_sel_hi:[1,0,1]
	v_pk_fma_f32 v[250:251], v[168:169], v[122:123], v[250:251] op_sel:[0,1,0]
	ds_read_b128 v[116:119], v176 offset:32
	ds_read_b128 v[120:123], v176 offset:112
	s_waitcnt lgkmcnt(9)
	v_pk_fma_f32 v[236:237], v[166:167], v[124:125], v[236:237] op_sel_hi:[1,0,1]
	v_pk_fma_f32 v[238:239], v[166:167], v[124:125], v[238:239] op_sel:[0,1,0]
	v_pk_fma_f32 v[240:241], v[166:167], v[126:127], v[240:241] op_sel_hi:[1,0,1]
	v_pk_fma_f32 v[242:243], v[166:167], v[126:127], v[242:243] op_sel:[0,1,0]
	v_pk_fma_f32 v[244:245], v[166:167], v[128:129], v[244:245] op_sel_hi:[1,0,1]
	v_pk_fma_f32 v[246:247], v[166:167], v[128:129], v[246:247] op_sel:[0,1,0]
	v_pk_fma_f32 v[248:249], v[166:167], v[130:131], v[248:249] op_sel_hi:[1,0,1]
	v_pk_fma_f32 v[250:251], v[166:167], v[130:131], v[250:251] op_sel:[0,1,0]
	ds_read_b128 v[124:127], v176 offset:48
	ds_read_b128 v[128:131], v176 offset:128
	ds_read_b64 v[166:167], v177
	s_waitcnt lgkmcnt(10)
	v_pk_mul_f32 v[172:173], v[236:237], v[132:133] op_sel_hi:[1,0]
	v_pk_mul_f32 v[174:175], v[238:239], v[132:133] op_sel:[0,1]
	v_pk_fma_f32 v[172:173], v[240:241], v[134:135], v[172:173] op_sel_hi:[1,0,1]
	v_pk_fma_f32 v[174:175], v[242:243], v[134:135], v[174:175] op_sel:[0,1,0]
	v_pk_fma_f32 v[172:173], v[244:245], v[136:137], v[172:173] op_sel_hi:[1,0,1]
	v_pk_fma_f32 v[174:175], v[246:247], v[136:137], v[174:175] op_sel:[0,1,0]
	v_pk_fma_f32 v[172:173], v[248:249], v[138:139], v[172:173] op_sel_hi:[1,0,1]
	v_pk_fma_f32 v[174:175], v[250:251], v[138:139], v[174:175] op_sel:[0,1,0]
	v_pk_add_f32 v[172:173], v[172:173], v[174:175]
	ds_write_b64 v254, v[172:173] offset:30720
	ds_read_b128 v[132:135], v176 offset:64
	ds_read_b128 v[136:139], v176 offset:144
	s_waitcnt lgkmcnt(2)
	s_barrier
	v_add_u32_e32 v252, s42, v252
	v_add_u32_e32 v253, s43, v253
	v_add_u32_e32 v254, s44, v254
	v_subrev_u32_e32 v176, s42, v176
	v_subrev_u32_e32 v177, s43, v177
	s_sub_i32 s42, 0, s42
	s_sub_i32 s43, 0, s43
	s_sub_i32 s44, 0, s44
	s_add_i32 s23, s23, 1
	s_cmpk_lg_u32 s23, 0x100
	s_cbranch_scc1 .LW_rloop
	s_setprio 0
	s_branch .LBB0_2062
